# v49 with 16384 (16 per wave) instead of 20480 w_ffn_out items in the FFN-in tail
# speedup vs baseline: 1.0010x; 1.0010x over previous
.LBB0_464:
	s_min_i32 s5, s84, 0x80
	v_readlane_b32 s0, v254, 0
	s_waitcnt vmcnt(0)
	v_lshrrev_b32_e32 v2, 6, v0
	s_mov_b32 s2, s0
	s_cmp_ge_i32 s0, s5
	s_mul_i32 s0, s0, 2
	v_add3_u32 v3, v2, s0, -1
	s_cselect_b64 vcc, -1, 0
	s_sub_i32 s0, s2, s5
	s_mul_i32 s4, s5, 2
	s_lshl_b32 s0, s0, 3
	s_add_i32 s0, s0, s4
	v_readlane_b32 s1, v254, 1
	v_add_u32_e32 v2, s0, v2
	v_add_u32_e32 v31, -64, v0
	s_movk_i32 s7, 0x80
	v_cmp_gt_u32_e64 s[0:1], s7, v31
	v_cndmask_b32_e32 v30, v3, v2, vcc
	s_mov_b32 s6, 0x18200
	s_cmpk_eq_u32 s84, 0x100
	s_cselect_b32 s6, 0x14200, s6
	s_or_b64 s[0:1], vcc, s[0:1]
	v_cmp_gt_i32_e32 vcc, s6, v30
	s_movk_i32 s3, 0x80
	s_and_b64 s[6:7], s[0:1], vcc
	s_and_saveexec_b64 s[0:1], s[6:7]
	s_cbranch_execz .LBB0_491
	s_sub_i32 s5, s84, s5
	v_lshlrev_b32_e32 v2, 8, v0
	s_lshl_b32 s33, s5, 3
	v_and_b32_e32 v2, 0x1c000, v2
	s_add_i32 s33, s33, s4
	v_add_u32_e32 v7, 0, v2
	v_lshlrev_b32_e32 v2, 4, v0
	v_and_b32_e32 v24, 0x70, v2
	v_lshlrev_b32_e32 v2, 3, v0
	s_add_u32 s6, s66, 0x8100000
	v_and_b32_e32 v2, 56, v2
	s_addc_u32 s7, s67, 0
	v_mul_u32_u24_e32 v6, 0x84, v2
	v_lshlrev_b32_e32 v2, 1, v2
	v_mov_b32_e32 v3, 0
	s_add_u32 s8, s66, 0x93400
	v_lshl_add_u64 v[12:13], s[66:67], 0, v[2:3]
	s_addc_u32 s9, s67, 0
	s_mov_b64 s[12:13], 0x6100000
	s_add_u32 s10, s66, 0xbc000
	v_lshl_add_u64 v[8:9], v[12:13], 0, s[12:13]
	s_mov_b64 s[12:13], 0x5100000
	s_mov_b64 s[4:5], 0x12d00000
	s_addc_u32 s11, s67, 0
	v_lshl_add_u64 v[10:11], v[12:13], 0, s[12:13]
	s_mov_b64 s[12:13], 0x4100000
	v_lshl_add_u64 v[4:5], v[12:13], 0, s[4:5]
	v_lshl_add_u64 v[12:13], v[12:13], 0, s[12:13]
	s_add_u32 s12, s66, 0x100000
	s_addc_u32 s13, s67, 0
	v_readlane_b32 s36, v254, 20
	v_lshrrev_b32_e32 v31, 3, v1
	s_add_u32 s14, s66, 0x8b400
	v_readlane_b32 s40, v254, 24
	v_readlane_b32 s41, v254, 25
	v_add_u32_e32 v26, v7, v24
	v_mul_u32_u24_e32 v27, 0x84, v31
	s_addc_u32 s15, s67, 0
	v_readlane_b32 s42, v254, 26
	v_readlane_b32 s43, v254, 27
	v_readlane_b32 s44, v254, 28
	v_readlane_b32 s45, v254, 29
	v_readlane_b32 s46, v254, 30
	v_readlane_b32 s47, v254, 31
	v_readlane_b32 s48, v254, 32
	v_readlane_b32 s49, v254, 33
	v_readlane_b32 s50, v254, 34
	v_readlane_b32 s51, v254, 35
	s_mov_b64 s[20:21], s[40:41]
	v_lshlrev_b32_e32 v2, 2, v31
	v_lshrrev_b32_e32 v1, 1, v1
	v_and_b32_e32 v40, 1, v0
	s_add_u32 s16, s66, 0xb4000
	v_mov_b32_e32 v25, v3
	v_readlane_b32 s37, v254, 21
	v_readlane_b32 s38, v254, 22
	v_readlane_b32 s39, v254, 23
	s_mov_b64 s[24:25], s[44:45]
	s_mov_b64 s[26:27], s[46:47]
	s_mov_b64 s[28:29], s[48:49]
	s_mov_b64 s[30:31], s[50:51]
	v_add_u32_e32 v44, v26, v27
	v_or_b32_e32 v32, 8, v31
	v_or_b32_e32 v33, 16, v31
	v_or_b32_e32 v34, 24, v31
	v_or_b32_e32 v35, 32, v31
	v_or_b32_e32 v36, 40, v31
	v_or_b32_e32 v37, 48, v31
	v_or_b32_e32 v38, 56, v31
	v_add3_u32 v39, v7, v6, v2
	v_lshlrev_b32_e32 v6, 5, v40
	v_lshl_add_u32 v41, v1, 2, v7
	v_mul_u32_u24_e32 v42, 0x1080, v40
	v_mov_b32_e32 v7, v3
	v_cmp_eq_u32_e64 s[4:5], 0, v40
	s_addc_u32 s17, s67, 0
	v_lshl_add_u64 v[14:15], s[60:61], 0, v[24:25]
	v_lshl_add_u64 v[16:17], s[54:55], 0, v[24:25]
	s_mov_b64 s[22:23], s[42:43]
	v_lshl_add_u64 v[18:19], s[30:31], 0, v[24:25]
	v_lshl_add_u64 v[20:21], s[26:27], 0, v[24:25]
	v_lshl_add_u64 v[22:23], s[24:25], 0, v[24:25]
	v_lshl_add_u64 v[24:25], s[28:29], 0, v[24:25]
	v_lshlrev_b32_e32 v43, 5, v30
	s_lshl_b32 s34, s33, 5
	s_mov_b64 s[18:19], 0
	s_movk_i32 s35, 0x3fff
	s_movk_i32 s36, 0x4fff
	s_movk_i32 s37, 0x5fff
	s_movk_i32 s38, 0x7fff
	s_mov_b32 s39, 0x12bff
	v_add_u32_e32 v45, 0x420, v44
	v_add_u32_e32 v46, 0x428, v44
	v_add_u32_e32 v47, 0x840, v44
	v_add_u32_e32 v48, 0x848, v44
	v_add_u32_e32 v49, 0xc60, v44
	v_add_u32_e32 v50, 0xc68, v44
	s_mov_b32 s40, 0xffff0000
	s_mov_b32 s41, 0xbe83
	s_movk_i32 s42, 0x2b0
	s_movk_i32 s43, 0x2a80
	s_mov_b32 s44, 0x42fe0000
	s_mov_b32 s45, 0xc0c0500
	s_mov_b32 s46, 0x181ff
	s_cmpk_eq_u32 s84, 0x100
	s_cselect_b32 s46, 0x141ff, s46
	v_add_u32_e32 v51, 0x1080, v44
	v_add_u32_e32 v52, 0x1088, v44
	v_add_u32_e32 v53, 0x14a0, v44
	v_add_u32_e32 v54, 0x14a8, v44
	v_add_u32_e32 v55, 0x18c0, v44
	s_branch .LBB0_468

.LBB0_1906:
	s_waitcnt vmcnt(0)
	s_mov_b32 s2, s86
	s_barrier
	s_cmpk_eq_u32 s84, 0x100
	s_cbranch_scc0 .Lwf_done
	v_readlane_b32 s94, v254, 0
	v_readfirstlane_b32 s95, v0
	s_nop 3
	s_cmpk_lt_u32 s94, 0x80
	s_cbranch_scc1 .Lwf_done
	s_lshr_b32 s95, s95, 6
	s_sub_u32 s94, s94, 0x80
	s_lshl_b32 s94, s94, 3
	s_add_u32 s94, s94, s95
	v_readlane_b32 s96, v254, 2
	v_readlane_b32 s97, v254, 3
	s_nop 3
	s_sub_u32 s96, s96, 0x28
	s_subb_u32 s97, s97, 0
	s_load_dwordx2 s[100:101], s[96:97], 0x0
	s_add_u32 s94, s94, 0x1600
	v_and_b32_e32 v2, 63, v0
	v_lshrrev_b32_e32 v3, 3, v2
	v_and_b32_e32 v4, 7, v2
	v_lshlrev_b32_e32 v5, 14, v3
	v_lshl_add_u32 v5, v4, 4, v5
	v_add_u32_e32 v6, 0x0, v5
	v_add_u32_e32 v7, 0x20000, v5
	v_add_u32_e32 v8, 0x40000, v5
	v_add_u32_e32 v9, 0x60000, v5
	v_add_u32_e32 v10, 0x80000, v5
	v_add_u32_e32 v11, 0xa0000, v5
	v_add_u32_e32 v12, 0xc0000, v5
	v_add_u32_e32 v13, 0xe0000, v5
	s_lshl_b32 s95, s95, 14
	v_mul_u32_u24_e32 v14, 0x84, v3
	v_lshl_add_u32 v14, v4, 4, v14
	v_add_u32_e32 v14, s95, v14
	v_mul_u32_u24_e32 v15, 0x420, v4
	v_lshl_add_u32 v15, v3, 2, v15
	v_add_u32_e32 v15, s95, v15
	v_mul_u32_u24_e32 v16, 0x5600, v3
	v_lshl_add_u32 v16, v4, 4, v16
	v_add_u32_e32 v17, 0x2b000, v16
	v_add_u32_e32 v18, 0x56000, v16
	v_add_u32_e32 v19, 0x81000, v16
	s_waitcnt lgkmcnt(0)
	s_mov_b32 s95, s94
	s_lshr_b32 vcc_lo, s95, 7
	s_and_b32 vcc_hi, s95, 0x7f
	s_lshl_b32 vcc_lo, vcc_lo, 20
	s_lshl_b32 vcc_hi, vcc_hi, 7
	s_add_u32 s96, s100, vcc_lo
	s_addc_u32 s97, s101, 0
	s_add_u32 s96, s96, vcc_hi
	s_addc_u32 s97, s97, 0
	global_load_dwordx4 v[20:23], v6, s[96:97]
	global_load_dwordx4 v[24:27], v7, s[96:97]
	global_load_dwordx4 v[28:31], v8, s[96:97]
	global_load_dwordx4 v[32:35], v9, s[96:97]
	global_load_dwordx4 v[36:39], v10, s[96:97]
	global_load_dwordx4 v[40:43], v11, s[96:97]
	global_load_dwordx4 v[44:47], v12, s[96:97]
	global_load_dwordx4 v[48:51], v13, s[96:97]
	s_add_u32 s95, s94, 0x400
	s_lshr_b32 vcc_lo, s95, 7
	s_and_b32 vcc_hi, s95, 0x7f
	s_lshl_b32 vcc_lo, vcc_lo, 20
	s_lshl_b32 vcc_hi, vcc_hi, 7
	s_add_u32 s96, s100, vcc_lo
	s_addc_u32 s97, s101, 0
	s_add_u32 s96, s96, vcc_hi
	s_addc_u32 s97, s97, 0
	global_load_dwordx4 v[100:103], v6, s[96:97]
	global_load_dwordx4 v[104:107], v7, s[96:97]
	global_load_dwordx4 v[108:111], v8, s[96:97]
	global_load_dwordx4 v[112:115], v9, s[96:97]
	global_load_dwordx4 v[116:119], v10, s[96:97]
	global_load_dwordx4 v[120:123], v11, s[96:97]
	global_load_dwordx4 v[124:127], v12, s[96:97]
	global_load_dwordx4 v[128:131], v13, s[96:97]
	s_waitcnt vmcnt(15)
	ds_write_b32 v14, v20 offset:0
	ds_write_b32 v14, v21 offset:4
	ds_write_b32 v14, v22 offset:8
	ds_write_b32 v14, v23 offset:12
	s_waitcnt vmcnt(14)
	ds_write_b32 v14, v24 offset:1056
	ds_write_b32 v14, v25 offset:1060
	ds_write_b32 v14, v26 offset:1064
	ds_write_b32 v14, v27 offset:1068
	s_waitcnt vmcnt(13)
	ds_write_b32 v14, v28 offset:2112
	ds_write_b32 v14, v29 offset:2116
	ds_write_b32 v14, v30 offset:2120
	ds_write_b32 v14, v31 offset:2124
	s_waitcnt vmcnt(12)
	ds_write_b32 v14, v32 offset:3168
	ds_write_b32 v14, v33 offset:3172
	ds_write_b32 v14, v34 offset:3176
	ds_write_b32 v14, v35 offset:3180
	s_waitcnt vmcnt(11)
	ds_write_b32 v14, v36 offset:4224
	ds_write_b32 v14, v37 offset:4228
	ds_write_b32 v14, v38 offset:4232
	ds_write_b32 v14, v39 offset:4236
	s_waitcnt vmcnt(10)
	ds_write_b32 v14, v40 offset:5280
	ds_write_b32 v14, v41 offset:5284
	ds_write_b32 v14, v42 offset:5288
	ds_write_b32 v14, v43 offset:5292
	s_waitcnt vmcnt(9)
	ds_write_b32 v14, v44 offset:6336
	ds_write_b32 v14, v45 offset:6340
	ds_write_b32 v14, v46 offset:6344
	ds_write_b32 v14, v47 offset:6348
	s_waitcnt vmcnt(8)
	ds_write_b32 v14, v48 offset:7392
	ds_write_b32 v14, v49 offset:7396
	ds_write_b32 v14, v50 offset:7400
	ds_write_b32 v14, v51 offset:7404
	s_add_u32 s95, s94, 0x800
	s_lshr_b32 vcc_lo, s95, 7
	s_and_b32 vcc_hi, s95, 0x7f
	s_lshl_b32 vcc_lo, vcc_lo, 20
	s_lshl_b32 vcc_hi, vcc_hi, 7
	s_add_u32 s96, s100, vcc_lo
	s_addc_u32 s97, s101, 0
	s_add_u32 s96, s96, vcc_hi
	s_addc_u32 s97, s97, 0
	global_load_dwordx4 v[20:23], v6, s[96:97]
	global_load_dwordx4 v[24:27], v7, s[96:97]
	global_load_dwordx4 v[28:31], v8, s[96:97]
	global_load_dwordx4 v[32:35], v9, s[96:97]
	global_load_dwordx4 v[36:39], v10, s[96:97]
	global_load_dwordx4 v[40:43], v11, s[96:97]
	global_load_dwordx4 v[44:47], v12, s[96:97]
	global_load_dwordx4 v[48:51], v13, s[96:97]
	ds_read2_b32 v[52:53], v15 offset0:0 offset1:33
	ds_read2_b32 v[54:55], v15 offset0:66 offset1:99
	ds_read2_b32 v[56:57], v15 offset0:132 offset1:165
	ds_read2_b32 v[58:59], v15 offset0:198 offset1:231
	ds_read2_b32 v[60:61], v15 offset0:8 offset1:41
	ds_read2_b32 v[62:63], v15 offset0:74 offset1:107
	ds_read2_b32 v[64:65], v15 offset0:140 offset1:173
	ds_read2_b32 v[66:67], v15 offset0:206 offset1:239
	ds_read2_b32 v[68:69], v15 offset0:16 offset1:49
	ds_read2_b32 v[70:71], v15 offset0:82 offset1:115
	ds_read2_b32 v[72:73], v15 offset0:148 offset1:181
	ds_read2_b32 v[74:75], v15 offset0:214 offset1:247
	ds_read2_b32 v[76:77], v15 offset0:24 offset1:57
	ds_read2_b32 v[78:79], v15 offset0:90 offset1:123
	ds_read2_b32 v[80:81], v15 offset0:156 offset1:189
	ds_read2_b32 v[82:83], v15 offset0:222 offset1:255
	s_mov_b32 s95, s94
	s_lshr_b32 vcc_lo, s95, 7
	s_and_b32 vcc_hi, s95, 0x7f
	s_mul_i32 vcc_hi, vcc_hi, 0xac000
	s_lshl_b32 vcc_lo, vcc_lo, 7
	s_add_u32 s98, s66, 0x12d00000
	s_addc_u32 s99, s67, 0
	s_add_u32 s98, s98, vcc_hi
	s_addc_u32 s99, s99, 0
	s_add_u32 s98, s98, vcc_lo
	s_addc_u32 s99, s99, 0
	s_waitcnt lgkmcnt(0)
	v_cvt_pk_bf16_f32 v84, v52, v53
	v_cvt_pk_bf16_f32 v85, v54, v55
	v_cvt_pk_bf16_f32 v86, v56, v57
	v_cvt_pk_bf16_f32 v87, v58, v59
	v_cvt_pk_bf16_f32 v88, v60, v61
	v_cvt_pk_bf16_f32 v89, v62, v63
	v_cvt_pk_bf16_f32 v90, v64, v65
	v_cvt_pk_bf16_f32 v91, v66, v67
	v_cvt_pk_bf16_f32 v92, v68, v69
	v_cvt_pk_bf16_f32 v93, v70, v71
	v_cvt_pk_bf16_f32 v94, v72, v73
	v_cvt_pk_bf16_f32 v95, v74, v75
	v_cvt_pk_bf16_f32 v96, v76, v77
	v_cvt_pk_bf16_f32 v97, v78, v79
	v_cvt_pk_bf16_f32 v98, v80, v81
	v_cvt_pk_bf16_f32 v99, v82, v83
	global_store_dwordx4 v16, v[84:87], s[98:99]
	global_store_dwordx4 v17, v[88:91], s[98:99]
	global_store_dwordx4 v18, v[92:95], s[98:99]
	global_store_dwordx4 v19, v[96:99], s[98:99]
	s_waitcnt vmcnt(19)
	ds_write_b32 v14, v100 offset:0
	ds_write_b32 v14, v101 offset:4
	ds_write_b32 v14, v102 offset:8
	ds_write_b32 v14, v103 offset:12
	s_waitcnt vmcnt(18)
	ds_write_b32 v14, v104 offset:1056
	ds_write_b32 v14, v105 offset:1060
	ds_write_b32 v14, v106 offset:1064
	ds_write_b32 v14, v107 offset:1068
	s_waitcnt vmcnt(17)
	ds_write_b32 v14, v108 offset:2112
	ds_write_b32 v14, v109 offset:2116
	ds_write_b32 v14, v110 offset:2120
	ds_write_b32 v14, v111 offset:2124
	s_waitcnt vmcnt(16)
	ds_write_b32 v14, v112 offset:3168
	ds_write_b32 v14, v113 offset:3172
	ds_write_b32 v14, v114 offset:3176
	ds_write_b32 v14, v115 offset:3180
	s_waitcnt vmcnt(15)
	ds_write_b32 v14, v116 offset:4224
	ds_write_b32 v14, v117 offset:4228
	ds_write_b32 v14, v118 offset:4232
	ds_write_b32 v14, v119 offset:4236
	s_waitcnt vmcnt(14)
	ds_write_b32 v14, v120 offset:5280
	ds_write_b32 v14, v121 offset:5284
	ds_write_b32 v14, v122 offset:5288
	ds_write_b32 v14, v123 offset:5292
	s_waitcnt vmcnt(13)
	ds_write_b32 v14, v124 offset:6336
	ds_write_b32 v14, v125 offset:6340
	ds_write_b32 v14, v126 offset:6344
	ds_write_b32 v14, v127 offset:6348
	s_waitcnt vmcnt(12)
	ds_write_b32 v14, v128 offset:7392
	ds_write_b32 v14, v129 offset:7396
	ds_write_b32 v14, v130 offset:7400
	ds_write_b32 v14, v131 offset:7404
	s_add_u32 s95, s94, 0xc00
	s_lshr_b32 vcc_lo, s95, 7
	s_and_b32 vcc_hi, s95, 0x7f
	s_lshl_b32 vcc_lo, vcc_lo, 20
	s_lshl_b32 vcc_hi, vcc_hi, 7
	s_add_u32 s96, s100, vcc_lo
	s_addc_u32 s97, s101, 0
	s_add_u32 s96, s96, vcc_hi
	s_addc_u32 s97, s97, 0
	global_load_dwordx4 v[100:103], v6, s[96:97]
	global_load_dwordx4 v[104:107], v7, s[96:97]
	global_load_dwordx4 v[108:111], v8, s[96:97]
	global_load_dwordx4 v[112:115], v9, s[96:97]
	global_load_dwordx4 v[116:119], v10, s[96:97]
	global_load_dwordx4 v[120:123], v11, s[96:97]
	global_load_dwordx4 v[124:127], v12, s[96:97]
	global_load_dwordx4 v[128:131], v13, s[96:97]
	ds_read2_b32 v[52:53], v15 offset0:0 offset1:33
	ds_read2_b32 v[54:55], v15 offset0:66 offset1:99
	ds_read2_b32 v[56:57], v15 offset0:132 offset1:165
	ds_read2_b32 v[58:59], v15 offset0:198 offset1:231
	ds_read2_b32 v[60:61], v15 offset0:8 offset1:41
	ds_read2_b32 v[62:63], v15 offset0:74 offset1:107
	ds_read2_b32 v[64:65], v15 offset0:140 offset1:173
	ds_read2_b32 v[66:67], v15 offset0:206 offset1:239
	ds_read2_b32 v[68:69], v15 offset0:16 offset1:49
	ds_read2_b32 v[70:71], v15 offset0:82 offset1:115
	ds_read2_b32 v[72:73], v15 offset0:148 offset1:181
	ds_read2_b32 v[74:75], v15 offset0:214 offset1:247
	ds_read2_b32 v[76:77], v15 offset0:24 offset1:57
	ds_read2_b32 v[78:79], v15 offset0:90 offset1:123
	ds_read2_b32 v[80:81], v15 offset0:156 offset1:189
	ds_read2_b32 v[82:83], v15 offset0:222 offset1:255
	s_add_u32 s95, s94, 0x400
	s_lshr_b32 vcc_lo, s95, 7
	s_and_b32 vcc_hi, s95, 0x7f
	s_mul_i32 vcc_hi, vcc_hi, 0xac000
	s_lshl_b32 vcc_lo, vcc_lo, 7
	s_add_u32 s98, s66, 0x12d00000
	s_addc_u32 s99, s67, 0
	s_add_u32 s98, s98, vcc_hi
	s_addc_u32 s99, s99, 0
	s_add_u32 s98, s98, vcc_lo
	s_addc_u32 s99, s99, 0
	s_waitcnt lgkmcnt(0)
	v_cvt_pk_bf16_f32 v84, v52, v53
	v_cvt_pk_bf16_f32 v85, v54, v55
	v_cvt_pk_bf16_f32 v86, v56, v57
	v_cvt_pk_bf16_f32 v87, v58, v59
	v_cvt_pk_bf16_f32 v88, v60, v61
	v_cvt_pk_bf16_f32 v89, v62, v63
	v_cvt_pk_bf16_f32 v90, v64, v65
	v_cvt_pk_bf16_f32 v91, v66, v67
	v_cvt_pk_bf16_f32 v92, v68, v69
	v_cvt_pk_bf16_f32 v93, v70, v71
	v_cvt_pk_bf16_f32 v94, v72, v73
	v_cvt_pk_bf16_f32 v95, v74, v75
	v_cvt_pk_bf16_f32 v96, v76, v77
	v_cvt_pk_bf16_f32 v97, v78, v79
	v_cvt_pk_bf16_f32 v98, v80, v81
	v_cvt_pk_bf16_f32 v99, v82, v83
	global_store_dwordx4 v16, v[84:87], s[98:99]
	global_store_dwordx4 v17, v[88:91], s[98:99]
	global_store_dwordx4 v18, v[92:95], s[98:99]
	global_store_dwordx4 v19, v[96:99], s[98:99]
	s_waitcnt vmcnt(23)
	ds_write_b32 v14, v20 offset:0
	ds_write_b32 v14, v21 offset:4
	ds_write_b32 v14, v22 offset:8
	ds_write_b32 v14, v23 offset:12
	s_waitcnt vmcnt(22)
	ds_write_b32 v14, v24 offset:1056
	ds_write_b32 v14, v25 offset:1060
	ds_write_b32 v14, v26 offset:1064
	ds_write_b32 v14, v27 offset:1068
	s_waitcnt vmcnt(21)
	ds_write_b32 v14, v28 offset:2112
	ds_write_b32 v14, v29 offset:2116
	ds_write_b32 v14, v30 offset:2120
	ds_write_b32 v14, v31 offset:2124
	s_waitcnt vmcnt(20)
	ds_write_b32 v14, v32 offset:3168
	ds_write_b32 v14, v33 offset:3172
	ds_write_b32 v14, v34 offset:3176
	ds_write_b32 v14, v35 offset:3180
	s_waitcnt vmcnt(19)
	ds_write_b32 v14, v36 offset:4224
	ds_write_b32 v14, v37 offset:4228
	ds_write_b32 v14, v38 offset:4232
	ds_write_b32 v14, v39 offset:4236
	s_waitcnt vmcnt(18)
	ds_write_b32 v14, v40 offset:5280
	ds_write_b32 v14, v41 offset:5284
	ds_write_b32 v14, v42 offset:5288
	ds_write_b32 v14, v43 offset:5292
	s_waitcnt vmcnt(17)
	ds_write_b32 v14, v44 offset:6336
	ds_write_b32 v14, v45 offset:6340
	ds_write_b32 v14, v46 offset:6344
	ds_write_b32 v14, v47 offset:6348
	s_waitcnt vmcnt(16)
	ds_write_b32 v14, v48 offset:7392
	ds_write_b32 v14, v49 offset:7396
	ds_write_b32 v14, v50 offset:7400
	ds_write_b32 v14, v51 offset:7404
	s_add_u32 s95, s94, 0x1000
	s_lshr_b32 vcc_lo, s95, 7
	s_and_b32 vcc_hi, s95, 0x7f
	s_lshl_b32 vcc_lo, vcc_lo, 20
	s_lshl_b32 vcc_hi, vcc_hi, 7
	s_add_u32 s96, s100, vcc_lo
	s_addc_u32 s97, s101, 0
	s_add_u32 s96, s96, vcc_hi
	s_addc_u32 s97, s97, 0
	global_load_dwordx4 v[20:23], v6, s[96:97]
	global_load_dwordx4 v[24:27], v7, s[96:97]
	global_load_dwordx4 v[28:31], v8, s[96:97]
	global_load_dwordx4 v[32:35], v9, s[96:97]
	global_load_dwordx4 v[36:39], v10, s[96:97]
	global_load_dwordx4 v[40:43], v11, s[96:97]
	global_load_dwordx4 v[44:47], v12, s[96:97]
	global_load_dwordx4 v[48:51], v13, s[96:97]
	ds_read2_b32 v[52:53], v15 offset0:0 offset1:33
	ds_read2_b32 v[54:55], v15 offset0:66 offset1:99
	ds_read2_b32 v[56:57], v15 offset0:132 offset1:165
	ds_read2_b32 v[58:59], v15 offset0:198 offset1:231
	ds_read2_b32 v[60:61], v15 offset0:8 offset1:41
	ds_read2_b32 v[62:63], v15 offset0:74 offset1:107
	ds_read2_b32 v[64:65], v15 offset0:140 offset1:173
	ds_read2_b32 v[66:67], v15 offset0:206 offset1:239
	ds_read2_b32 v[68:69], v15 offset0:16 offset1:49
	ds_read2_b32 v[70:71], v15 offset0:82 offset1:115
	ds_read2_b32 v[72:73], v15 offset0:148 offset1:181
	ds_read2_b32 v[74:75], v15 offset0:214 offset1:247
	ds_read2_b32 v[76:77], v15 offset0:24 offset1:57
	ds_read2_b32 v[78:79], v15 offset0:90 offset1:123
	ds_read2_b32 v[80:81], v15 offset0:156 offset1:189
	ds_read2_b32 v[82:83], v15 offset0:222 offset1:255
	s_add_u32 s95, s94, 0x800
	s_lshr_b32 vcc_lo, s95, 7
	s_and_b32 vcc_hi, s95, 0x7f
	s_mul_i32 vcc_hi, vcc_hi, 0xac000
	s_lshl_b32 vcc_lo, vcc_lo, 7
	s_add_u32 s98, s66, 0x12d00000
	s_addc_u32 s99, s67, 0
	s_add_u32 s98, s98, vcc_hi
	s_addc_u32 s99, s99, 0
	s_add_u32 s98, s98, vcc_lo
	s_addc_u32 s99, s99, 0
	s_waitcnt lgkmcnt(0)
	v_cvt_pk_bf16_f32 v84, v52, v53
	v_cvt_pk_bf16_f32 v85, v54, v55
	v_cvt_pk_bf16_f32 v86, v56, v57
	v_cvt_pk_bf16_f32 v87, v58, v59
	v_cvt_pk_bf16_f32 v88, v60, v61
	v_cvt_pk_bf16_f32 v89, v62, v63
	v_cvt_pk_bf16_f32 v90, v64, v65
	v_cvt_pk_bf16_f32 v91, v66, v67
	v_cvt_pk_bf16_f32 v92, v68, v69
	v_cvt_pk_bf16_f32 v93, v70, v71
	v_cvt_pk_bf16_f32 v94, v72, v73
	v_cvt_pk_bf16_f32 v95, v74, v75
	v_cvt_pk_bf16_f32 v96, v76, v77
	v_cvt_pk_bf16_f32 v97, v78, v79
	v_cvt_pk_bf16_f32 v98, v80, v81
	v_cvt_pk_bf16_f32 v99, v82, v83
	global_store_dwordx4 v16, v[84:87], s[98:99]
	global_store_dwordx4 v17, v[88:91], s[98:99]
	global_store_dwordx4 v18, v[92:95], s[98:99]
	global_store_dwordx4 v19, v[96:99], s[98:99]
	s_waitcnt vmcnt(23)
	ds_write_b32 v14, v100 offset:0
	ds_write_b32 v14, v101 offset:4
	ds_write_b32 v14, v102 offset:8
	ds_write_b32 v14, v103 offset:12
	s_waitcnt vmcnt(22)
	ds_write_b32 v14, v104 offset:1056
	ds_write_b32 v14, v105 offset:1060
	ds_write_b32 v14, v106 offset:1064
	ds_write_b32 v14, v107 offset:1068
	s_waitcnt vmcnt(21)
	ds_write_b32 v14, v108 offset:2112
	ds_write_b32 v14, v109 offset:2116
	ds_write_b32 v14, v110 offset:2120
	ds_write_b32 v14, v111 offset:2124
	s_waitcnt vmcnt(20)
	ds_write_b32 v14, v112 offset:3168
	ds_write_b32 v14, v113 offset:3172
	ds_write_b32 v14, v114 offset:3176
	ds_write_b32 v14, v115 offset:3180
	s_waitcnt vmcnt(19)
	ds_write_b32 v14, v116 offset:4224
	ds_write_b32 v14, v117 offset:4228
	ds_write_b32 v14, v118 offset:4232
	ds_write_b32 v14, v119 offset:4236
	s_waitcnt vmcnt(18)
	ds_write_b32 v14, v120 offset:5280
	ds_write_b32 v14, v121 offset:5284
	ds_write_b32 v14, v122 offset:5288
	ds_write_b32 v14, v123 offset:5292
	s_waitcnt vmcnt(17)
	ds_write_b32 v14, v124 offset:6336
	ds_write_b32 v14, v125 offset:6340
	ds_write_b32 v14, v126 offset:6344
	ds_write_b32 v14, v127 offset:6348
	s_waitcnt vmcnt(16)
	ds_write_b32 v14, v128 offset:7392
	ds_write_b32 v14, v129 offset:7396
	ds_write_b32 v14, v130 offset:7400
	ds_write_b32 v14, v131 offset:7404
	s_add_u32 s95, s94, 0x1400
	s_lshr_b32 vcc_lo, s95, 7
	s_and_b32 vcc_hi, s95, 0x7f
	s_lshl_b32 vcc_lo, vcc_lo, 20
	s_lshl_b32 vcc_hi, vcc_hi, 7
	s_add_u32 s96, s100, vcc_lo
	s_addc_u32 s97, s101, 0
	s_add_u32 s96, s96, vcc_hi
	s_addc_u32 s97, s97, 0
	global_load_dwordx4 v[100:103], v6, s[96:97]
	global_load_dwordx4 v[104:107], v7, s[96:97]
	global_load_dwordx4 v[108:111], v8, s[96:97]
	global_load_dwordx4 v[112:115], v9, s[96:97]
	global_load_dwordx4 v[116:119], v10, s[96:97]
	global_load_dwordx4 v[120:123], v11, s[96:97]
	global_load_dwordx4 v[124:127], v12, s[96:97]
	global_load_dwordx4 v[128:131], v13, s[96:97]
	ds_read2_b32 v[52:53], v15 offset0:0 offset1:33
	ds_read2_b32 v[54:55], v15 offset0:66 offset1:99
	ds_read2_b32 v[56:57], v15 offset0:132 offset1:165
	ds_read2_b32 v[58:59], v15 offset0:198 offset1:231
	ds_read2_b32 v[60:61], v15 offset0:8 offset1:41
	ds_read2_b32 v[62:63], v15 offset0:74 offset1:107
	ds_read2_b32 v[64:65], v15 offset0:140 offset1:173
	ds_read2_b32 v[66:67], v15 offset0:206 offset1:239
	ds_read2_b32 v[68:69], v15 offset0:16 offset1:49
	ds_read2_b32 v[70:71], v15 offset0:82 offset1:115
	ds_read2_b32 v[72:73], v15 offset0:148 offset1:181
	ds_read2_b32 v[74:75], v15 offset0:214 offset1:247
	ds_read2_b32 v[76:77], v15 offset0:24 offset1:57
	ds_read2_b32 v[78:79], v15 offset0:90 offset1:123
	ds_read2_b32 v[80:81], v15 offset0:156 offset1:189
	ds_read2_b32 v[82:83], v15 offset0:222 offset1:255
	s_add_u32 s95, s94, 0xc00
	s_lshr_b32 vcc_lo, s95, 7
	s_and_b32 vcc_hi, s95, 0x7f
	s_mul_i32 vcc_hi, vcc_hi, 0xac000
	s_lshl_b32 vcc_lo, vcc_lo, 7
	s_add_u32 s98, s66, 0x12d00000
	s_addc_u32 s99, s67, 0
	s_add_u32 s98, s98, vcc_hi
	s_addc_u32 s99, s99, 0
	s_add_u32 s98, s98, vcc_lo
	s_addc_u32 s99, s99, 0
	s_waitcnt lgkmcnt(0)
	v_cvt_pk_bf16_f32 v84, v52, v53
	v_cvt_pk_bf16_f32 v85, v54, v55
	v_cvt_pk_bf16_f32 v86, v56, v57
	v_cvt_pk_bf16_f32 v87, v58, v59
	v_cvt_pk_bf16_f32 v88, v60, v61
	v_cvt_pk_bf16_f32 v89, v62, v63
	v_cvt_pk_bf16_f32 v90, v64, v65
	v_cvt_pk_bf16_f32 v91, v66, v67
	v_cvt_pk_bf16_f32 v92, v68, v69
	v_cvt_pk_bf16_f32 v93, v70, v71
	v_cvt_pk_bf16_f32 v94, v72, v73
	v_cvt_pk_bf16_f32 v95, v74, v75
	v_cvt_pk_bf16_f32 v96, v76, v77
	v_cvt_pk_bf16_f32 v97, v78, v79
	v_cvt_pk_bf16_f32 v98, v80, v81
	v_cvt_pk_bf16_f32 v99, v82, v83
	global_store_dwordx4 v16, v[84:87], s[98:99]
	global_store_dwordx4 v17, v[88:91], s[98:99]
	global_store_dwordx4 v18, v[92:95], s[98:99]
	global_store_dwordx4 v19, v[96:99], s[98:99]
	s_waitcnt vmcnt(23)
	ds_write_b32 v14, v20 offset:0
	ds_write_b32 v14, v21 offset:4
	ds_write_b32 v14, v22 offset:8
	ds_write_b32 v14, v23 offset:12
	s_waitcnt vmcnt(22)
	ds_write_b32 v14, v24 offset:1056
	ds_write_b32 v14, v25 offset:1060
	ds_write_b32 v14, v26 offset:1064
	ds_write_b32 v14, v27 offset:1068
	s_waitcnt vmcnt(21)
	ds_write_b32 v14, v28 offset:2112
	ds_write_b32 v14, v29 offset:2116
	ds_write_b32 v14, v30 offset:2120
	ds_write_b32 v14, v31 offset:2124
	s_waitcnt vmcnt(20)
	ds_write_b32 v14, v32 offset:3168
	ds_write_b32 v14, v33 offset:3172
	ds_write_b32 v14, v34 offset:3176
	ds_write_b32 v14, v35 offset:3180
	s_waitcnt vmcnt(19)
	ds_write_b32 v14, v36 offset:4224
	ds_write_b32 v14, v37 offset:4228
	ds_write_b32 v14, v38 offset:4232
	ds_write_b32 v14, v39 offset:4236
	s_waitcnt vmcnt(18)
	ds_write_b32 v14, v40 offset:5280
	ds_write_b32 v14, v41 offset:5284
	ds_write_b32 v14, v42 offset:5288
	ds_write_b32 v14, v43 offset:5292
	s_waitcnt vmcnt(17)
	ds_write_b32 v14, v44 offset:6336
	ds_write_b32 v14, v45 offset:6340
	ds_write_b32 v14, v46 offset:6344
	ds_write_b32 v14, v47 offset:6348
	s_waitcnt vmcnt(16)
	ds_write_b32 v14, v48 offset:7392
	ds_write_b32 v14, v49 offset:7396
	ds_write_b32 v14, v50 offset:7400
	ds_write_b32 v14, v51 offset:7404
	s_add_u32 s95, s94, 0x1800
	s_lshr_b32 vcc_lo, s95, 7
	s_and_b32 vcc_hi, s95, 0x7f
	s_lshl_b32 vcc_lo, vcc_lo, 20
	s_lshl_b32 vcc_hi, vcc_hi, 7
	s_add_u32 s96, s100, vcc_lo
	s_addc_u32 s97, s101, 0
	s_add_u32 s96, s96, vcc_hi
	s_addc_u32 s97, s97, 0
	global_load_dwordx4 v[20:23], v6, s[96:97]
	global_load_dwordx4 v[24:27], v7, s[96:97]
	global_load_dwordx4 v[28:31], v8, s[96:97]
	global_load_dwordx4 v[32:35], v9, s[96:97]
	global_load_dwordx4 v[36:39], v10, s[96:97]
	global_load_dwordx4 v[40:43], v11, s[96:97]
	global_load_dwordx4 v[44:47], v12, s[96:97]
	global_load_dwordx4 v[48:51], v13, s[96:97]
	ds_read2_b32 v[52:53], v15 offset0:0 offset1:33
	ds_read2_b32 v[54:55], v15 offset0:66 offset1:99
	ds_read2_b32 v[56:57], v15 offset0:132 offset1:165
	ds_read2_b32 v[58:59], v15 offset0:198 offset1:231
	ds_read2_b32 v[60:61], v15 offset0:8 offset1:41
	ds_read2_b32 v[62:63], v15 offset0:74 offset1:107
	ds_read2_b32 v[64:65], v15 offset0:140 offset1:173
	ds_read2_b32 v[66:67], v15 offset0:206 offset1:239
	ds_read2_b32 v[68:69], v15 offset0:16 offset1:49
	ds_read2_b32 v[70:71], v15 offset0:82 offset1:115
	ds_read2_b32 v[72:73], v15 offset0:148 offset1:181
	ds_read2_b32 v[74:75], v15 offset0:214 offset1:247
	ds_read2_b32 v[76:77], v15 offset0:24 offset1:57
	ds_read2_b32 v[78:79], v15 offset0:90 offset1:123
	ds_read2_b32 v[80:81], v15 offset0:156 offset1:189
	ds_read2_b32 v[82:83], v15 offset0:222 offset1:255
	s_add_u32 s95, s94, 0x1000
	s_lshr_b32 vcc_lo, s95, 7
	s_and_b32 vcc_hi, s95, 0x7f
	s_mul_i32 vcc_hi, vcc_hi, 0xac000
	s_lshl_b32 vcc_lo, vcc_lo, 7
	s_add_u32 s98, s66, 0x12d00000
	s_addc_u32 s99, s67, 0
	s_add_u32 s98, s98, vcc_hi
	s_addc_u32 s99, s99, 0
	s_add_u32 s98, s98, vcc_lo
	s_addc_u32 s99, s99, 0
	s_waitcnt lgkmcnt(0)
	v_cvt_pk_bf16_f32 v84, v52, v53
	v_cvt_pk_bf16_f32 v85, v54, v55
	v_cvt_pk_bf16_f32 v86, v56, v57
	v_cvt_pk_bf16_f32 v87, v58, v59
	v_cvt_pk_bf16_f32 v88, v60, v61
	v_cvt_pk_bf16_f32 v89, v62, v63
	v_cvt_pk_bf16_f32 v90, v64, v65
	v_cvt_pk_bf16_f32 v91, v66, v67
	v_cvt_pk_bf16_f32 v92, v68, v69
	v_cvt_pk_bf16_f32 v93, v70, v71
	v_cvt_pk_bf16_f32 v94, v72, v73
	v_cvt_pk_bf16_f32 v95, v74, v75
	v_cvt_pk_bf16_f32 v96, v76, v77
	v_cvt_pk_bf16_f32 v97, v78, v79
	v_cvt_pk_bf16_f32 v98, v80, v81
	v_cvt_pk_bf16_f32 v99, v82, v83
	global_store_dwordx4 v16, v[84:87], s[98:99]
	global_store_dwordx4 v17, v[88:91], s[98:99]
	global_store_dwordx4 v18, v[92:95], s[98:99]
	global_store_dwordx4 v19, v[96:99], s[98:99]
	s_waitcnt vmcnt(23)
	ds_write_b32 v14, v100 offset:0
	ds_write_b32 v14, v101 offset:4
	ds_write_b32 v14, v102 offset:8
	ds_write_b32 v14, v103 offset:12
	s_waitcnt vmcnt(22)
	ds_write_b32 v14, v104 offset:1056
	ds_write_b32 v14, v105 offset:1060
	ds_write_b32 v14, v106 offset:1064
	ds_write_b32 v14, v107 offset:1068
	s_waitcnt vmcnt(21)
	ds_write_b32 v14, v108 offset:2112
	ds_write_b32 v14, v109 offset:2116
	ds_write_b32 v14, v110 offset:2120
	ds_write_b32 v14, v111 offset:2124
	s_waitcnt vmcnt(20)
	ds_write_b32 v14, v112 offset:3168
	ds_write_b32 v14, v113 offset:3172
	ds_write_b32 v14, v114 offset:3176
	ds_write_b32 v14, v115 offset:3180
	s_waitcnt vmcnt(19)
	ds_write_b32 v14, v116 offset:4224
	ds_write_b32 v14, v117 offset:4228
	ds_write_b32 v14, v118 offset:4232
	ds_write_b32 v14, v119 offset:4236
	s_waitcnt vmcnt(18)
	ds_write_b32 v14, v120 offset:5280
	ds_write_b32 v14, v121 offset:5284
	ds_write_b32 v14, v122 offset:5288
	ds_write_b32 v14, v123 offset:5292
	s_waitcnt vmcnt(17)
	ds_write_b32 v14, v124 offset:6336
	ds_write_b32 v14, v125 offset:6340
	ds_write_b32 v14, v126 offset:6344
	ds_write_b32 v14, v127 offset:6348
	s_waitcnt vmcnt(16)
	ds_write_b32 v14, v128 offset:7392
	ds_write_b32 v14, v129 offset:7396
	ds_write_b32 v14, v130 offset:7400
	ds_write_b32 v14, v131 offset:7404
	s_add_u32 s95, s94, 0x1c00
	s_lshr_b32 vcc_lo, s95, 7
	s_and_b32 vcc_hi, s95, 0x7f
	s_lshl_b32 vcc_lo, vcc_lo, 20
	s_lshl_b32 vcc_hi, vcc_hi, 7
	s_add_u32 s96, s100, vcc_lo
	s_addc_u32 s97, s101, 0
	s_add_u32 s96, s96, vcc_hi
	s_addc_u32 s97, s97, 0
	global_load_dwordx4 v[100:103], v6, s[96:97]
	global_load_dwordx4 v[104:107], v7, s[96:97]
	global_load_dwordx4 v[108:111], v8, s[96:97]
	global_load_dwordx4 v[112:115], v9, s[96:97]
	global_load_dwordx4 v[116:119], v10, s[96:97]
	global_load_dwordx4 v[120:123], v11, s[96:97]
	global_load_dwordx4 v[124:127], v12, s[96:97]
	global_load_dwordx4 v[128:131], v13, s[96:97]
	ds_read2_b32 v[52:53], v15 offset0:0 offset1:33
	ds_read2_b32 v[54:55], v15 offset0:66 offset1:99
	ds_read2_b32 v[56:57], v15 offset0:132 offset1:165
	ds_read2_b32 v[58:59], v15 offset0:198 offset1:231
	ds_read2_b32 v[60:61], v15 offset0:8 offset1:41
	ds_read2_b32 v[62:63], v15 offset0:74 offset1:107
	ds_read2_b32 v[64:65], v15 offset0:140 offset1:173
	ds_read2_b32 v[66:67], v15 offset0:206 offset1:239
	ds_read2_b32 v[68:69], v15 offset0:16 offset1:49
	ds_read2_b32 v[70:71], v15 offset0:82 offset1:115
	ds_read2_b32 v[72:73], v15 offset0:148 offset1:181
	ds_read2_b32 v[74:75], v15 offset0:214 offset1:247
	ds_read2_b32 v[76:77], v15 offset0:24 offset1:57
	ds_read2_b32 v[78:79], v15 offset0:90 offset1:123
	ds_read2_b32 v[80:81], v15 offset0:156 offset1:189
	ds_read2_b32 v[82:83], v15 offset0:222 offset1:255
	s_add_u32 s95, s94, 0x1400
	s_lshr_b32 vcc_lo, s95, 7
	s_and_b32 vcc_hi, s95, 0x7f
	s_mul_i32 vcc_hi, vcc_hi, 0xac000
	s_lshl_b32 vcc_lo, vcc_lo, 7
	s_add_u32 s98, s66, 0x12d00000
	s_addc_u32 s99, s67, 0
	s_add_u32 s98, s98, vcc_hi
	s_addc_u32 s99, s99, 0
	s_add_u32 s98, s98, vcc_lo
	s_addc_u32 s99, s99, 0
	s_waitcnt lgkmcnt(0)
	v_cvt_pk_bf16_f32 v84, v52, v53
	v_cvt_pk_bf16_f32 v85, v54, v55
	v_cvt_pk_bf16_f32 v86, v56, v57
	v_cvt_pk_bf16_f32 v87, v58, v59
	v_cvt_pk_bf16_f32 v88, v60, v61
	v_cvt_pk_bf16_f32 v89, v62, v63
	v_cvt_pk_bf16_f32 v90, v64, v65
	v_cvt_pk_bf16_f32 v91, v66, v67
	v_cvt_pk_bf16_f32 v92, v68, v69
	v_cvt_pk_bf16_f32 v93, v70, v71
	v_cvt_pk_bf16_f32 v94, v72, v73
	v_cvt_pk_bf16_f32 v95, v74, v75
	v_cvt_pk_bf16_f32 v96, v76, v77
	v_cvt_pk_bf16_f32 v97, v78, v79
	v_cvt_pk_bf16_f32 v98, v80, v81
	v_cvt_pk_bf16_f32 v99, v82, v83
	global_store_dwordx4 v16, v[84:87], s[98:99]
	global_store_dwordx4 v17, v[88:91], s[98:99]
	global_store_dwordx4 v18, v[92:95], s[98:99]
	global_store_dwordx4 v19, v[96:99], s[98:99]
	s_waitcnt vmcnt(23)
	ds_write_b32 v14, v20 offset:0
	ds_write_b32 v14, v21 offset:4
	ds_write_b32 v14, v22 offset:8
	ds_write_b32 v14, v23 offset:12
	s_waitcnt vmcnt(22)
	ds_write_b32 v14, v24 offset:1056
	ds_write_b32 v14, v25 offset:1060
	ds_write_b32 v14, v26 offset:1064
	ds_write_b32 v14, v27 offset:1068
	s_waitcnt vmcnt(21)
	ds_write_b32 v14, v28 offset:2112
	ds_write_b32 v14, v29 offset:2116
	ds_write_b32 v14, v30 offset:2120
	ds_write_b32 v14, v31 offset:2124
	s_waitcnt vmcnt(20)
	ds_write_b32 v14, v32 offset:3168
	ds_write_b32 v14, v33 offset:3172
	ds_write_b32 v14, v34 offset:3176
	ds_write_b32 v14, v35 offset:3180
	s_waitcnt vmcnt(19)
	ds_write_b32 v14, v36 offset:4224
	ds_write_b32 v14, v37 offset:4228
	ds_write_b32 v14, v38 offset:4232
	ds_write_b32 v14, v39 offset:4236
	s_waitcnt vmcnt(18)
	ds_write_b32 v14, v40 offset:5280
	ds_write_b32 v14, v41 offset:5284
	ds_write_b32 v14, v42 offset:5288
	ds_write_b32 v14, v43 offset:5292
	s_waitcnt vmcnt(17)
	ds_write_b32 v14, v44 offset:6336
	ds_write_b32 v14, v45 offset:6340
	ds_write_b32 v14, v46 offset:6344
	ds_write_b32 v14, v47 offset:6348
	s_waitcnt vmcnt(16)
	ds_write_b32 v14, v48 offset:7392
	ds_write_b32 v14, v49 offset:7396
	ds_write_b32 v14, v50 offset:7400
	ds_write_b32 v14, v51 offset:7404
	s_add_u32 s95, s94, 0x2000
	s_lshr_b32 vcc_lo, s95, 7
	s_and_b32 vcc_hi, s95, 0x7f
	s_lshl_b32 vcc_lo, vcc_lo, 20
	s_lshl_b32 vcc_hi, vcc_hi, 7
	s_add_u32 s96, s100, vcc_lo
	s_addc_u32 s97, s101, 0
	s_add_u32 s96, s96, vcc_hi
	s_addc_u32 s97, s97, 0
	global_load_dwordx4 v[20:23], v6, s[96:97]
	global_load_dwordx4 v[24:27], v7, s[96:97]
	global_load_dwordx4 v[28:31], v8, s[96:97]
	global_load_dwordx4 v[32:35], v9, s[96:97]
	global_load_dwordx4 v[36:39], v10, s[96:97]
	global_load_dwordx4 v[40:43], v11, s[96:97]
	global_load_dwordx4 v[44:47], v12, s[96:97]
	global_load_dwordx4 v[48:51], v13, s[96:97]
	ds_read2_b32 v[52:53], v15 offset0:0 offset1:33
	ds_read2_b32 v[54:55], v15 offset0:66 offset1:99
	ds_read2_b32 v[56:57], v15 offset0:132 offset1:165
	ds_read2_b32 v[58:59], v15 offset0:198 offset1:231
	ds_read2_b32 v[60:61], v15 offset0:8 offset1:41
	ds_read2_b32 v[62:63], v15 offset0:74 offset1:107
	ds_read2_b32 v[64:65], v15 offset0:140 offset1:173
	ds_read2_b32 v[66:67], v15 offset0:206 offset1:239
	ds_read2_b32 v[68:69], v15 offset0:16 offset1:49
	ds_read2_b32 v[70:71], v15 offset0:82 offset1:115
	ds_read2_b32 v[72:73], v15 offset0:148 offset1:181
	ds_read2_b32 v[74:75], v15 offset0:214 offset1:247
	ds_read2_b32 v[76:77], v15 offset0:24 offset1:57
	ds_read2_b32 v[78:79], v15 offset0:90 offset1:123
	ds_read2_b32 v[80:81], v15 offset0:156 offset1:189
	ds_read2_b32 v[82:83], v15 offset0:222 offset1:255
	s_add_u32 s95, s94, 0x1800
	s_lshr_b32 vcc_lo, s95, 7
	s_and_b32 vcc_hi, s95, 0x7f
	s_mul_i32 vcc_hi, vcc_hi, 0xac000
	s_lshl_b32 vcc_lo, vcc_lo, 7
	s_add_u32 s98, s66, 0x12d00000
	s_addc_u32 s99, s67, 0
	s_add_u32 s98, s98, vcc_hi
	s_addc_u32 s99, s99, 0
	s_add_u32 s98, s98, vcc_lo
	s_addc_u32 s99, s99, 0
	s_waitcnt lgkmcnt(0)
	v_cvt_pk_bf16_f32 v84, v52, v53
	v_cvt_pk_bf16_f32 v85, v54, v55
	v_cvt_pk_bf16_f32 v86, v56, v57
	v_cvt_pk_bf16_f32 v87, v58, v59
	v_cvt_pk_bf16_f32 v88, v60, v61
	v_cvt_pk_bf16_f32 v89, v62, v63
	v_cvt_pk_bf16_f32 v90, v64, v65
	v_cvt_pk_bf16_f32 v91, v66, v67
	v_cvt_pk_bf16_f32 v92, v68, v69
	v_cvt_pk_bf16_f32 v93, v70, v71
	v_cvt_pk_bf16_f32 v94, v72, v73
	v_cvt_pk_bf16_f32 v95, v74, v75
	v_cvt_pk_bf16_f32 v96, v76, v77
	v_cvt_pk_bf16_f32 v97, v78, v79
	v_cvt_pk_bf16_f32 v98, v80, v81
	v_cvt_pk_bf16_f32 v99, v82, v83
	global_store_dwordx4 v16, v[84:87], s[98:99]
	global_store_dwordx4 v17, v[88:91], s[98:99]
	global_store_dwordx4 v18, v[92:95], s[98:99]
	global_store_dwordx4 v19, v[96:99], s[98:99]
	s_waitcnt vmcnt(23)
	ds_write_b32 v14, v100 offset:0
	ds_write_b32 v14, v101 offset:4
	ds_write_b32 v14, v102 offset:8
	ds_write_b32 v14, v103 offset:12
	s_waitcnt vmcnt(22)
	ds_write_b32 v14, v104 offset:1056
	ds_write_b32 v14, v105 offset:1060
	ds_write_b32 v14, v106 offset:1064
	ds_write_b32 v14, v107 offset:1068
	s_waitcnt vmcnt(21)
	ds_write_b32 v14, v108 offset:2112
	ds_write_b32 v14, v109 offset:2116
	ds_write_b32 v14, v110 offset:2120
	ds_write_b32 v14, v111 offset:2124
	s_waitcnt vmcnt(20)
	ds_write_b32 v14, v112 offset:3168
	ds_write_b32 v14, v113 offset:3172
	ds_write_b32 v14, v114 offset:3176
	ds_write_b32 v14, v115 offset:3180
	s_waitcnt vmcnt(19)
	ds_write_b32 v14, v116 offset:4224
	ds_write_b32 v14, v117 offset:4228
	ds_write_b32 v14, v118 offset:4232
	ds_write_b32 v14, v119 offset:4236
	s_waitcnt vmcnt(18)
	ds_write_b32 v14, v120 offset:5280
	ds_write_b32 v14, v121 offset:5284
	ds_write_b32 v14, v122 offset:5288
	ds_write_b32 v14, v123 offset:5292
	s_waitcnt vmcnt(17)
	ds_write_b32 v14, v124 offset:6336
	ds_write_b32 v14, v125 offset:6340
	ds_write_b32 v14, v126 offset:6344
	ds_write_b32 v14, v127 offset:6348
	s_waitcnt vmcnt(16)
	ds_write_b32 v14, v128 offset:7392
	ds_write_b32 v14, v129 offset:7396
	ds_write_b32 v14, v130 offset:7400
	ds_write_b32 v14, v131 offset:7404
	s_add_u32 s95, s94, 0x2400
	s_lshr_b32 vcc_lo, s95, 7
	s_and_b32 vcc_hi, s95, 0x7f
	s_lshl_b32 vcc_lo, vcc_lo, 20
	s_lshl_b32 vcc_hi, vcc_hi, 7
	s_add_u32 s96, s100, vcc_lo
	s_addc_u32 s97, s101, 0
	s_add_u32 s96, s96, vcc_hi
	s_addc_u32 s97, s97, 0
	global_load_dwordx4 v[100:103], v6, s[96:97]
	global_load_dwordx4 v[104:107], v7, s[96:97]
	global_load_dwordx4 v[108:111], v8, s[96:97]
	global_load_dwordx4 v[112:115], v9, s[96:97]
	global_load_dwordx4 v[116:119], v10, s[96:97]
	global_load_dwordx4 v[120:123], v11, s[96:97]
	global_load_dwordx4 v[124:127], v12, s[96:97]
	global_load_dwordx4 v[128:131], v13, s[96:97]
	ds_read2_b32 v[52:53], v15 offset0:0 offset1:33
	ds_read2_b32 v[54:55], v15 offset0:66 offset1:99
	ds_read2_b32 v[56:57], v15 offset0:132 offset1:165
	ds_read2_b32 v[58:59], v15 offset0:198 offset1:231
	ds_read2_b32 v[60:61], v15 offset0:8 offset1:41
	ds_read2_b32 v[62:63], v15 offset0:74 offset1:107
	ds_read2_b32 v[64:65], v15 offset0:140 offset1:173
	ds_read2_b32 v[66:67], v15 offset0:206 offset1:239
	ds_read2_b32 v[68:69], v15 offset0:16 offset1:49
	ds_read2_b32 v[70:71], v15 offset0:82 offset1:115
	ds_read2_b32 v[72:73], v15 offset0:148 offset1:181
	ds_read2_b32 v[74:75], v15 offset0:214 offset1:247
	ds_read2_b32 v[76:77], v15 offset0:24 offset1:57
	ds_read2_b32 v[78:79], v15 offset0:90 offset1:123
	ds_read2_b32 v[80:81], v15 offset0:156 offset1:189
	ds_read2_b32 v[82:83], v15 offset0:222 offset1:255
	s_add_u32 s95, s94, 0x1c00
	s_lshr_b32 vcc_lo, s95, 7
	s_and_b32 vcc_hi, s95, 0x7f
	s_mul_i32 vcc_hi, vcc_hi, 0xac000
	s_lshl_b32 vcc_lo, vcc_lo, 7
	s_add_u32 s98, s66, 0x12d00000
	s_addc_u32 s99, s67, 0
	s_add_u32 s98, s98, vcc_hi
	s_addc_u32 s99, s99, 0
	s_add_u32 s98, s98, vcc_lo
	s_addc_u32 s99, s99, 0
	s_waitcnt lgkmcnt(0)
	v_cvt_pk_bf16_f32 v84, v52, v53
	v_cvt_pk_bf16_f32 v85, v54, v55
	v_cvt_pk_bf16_f32 v86, v56, v57
	v_cvt_pk_bf16_f32 v87, v58, v59
	v_cvt_pk_bf16_f32 v88, v60, v61
	v_cvt_pk_bf16_f32 v89, v62, v63
	v_cvt_pk_bf16_f32 v90, v64, v65
	v_cvt_pk_bf16_f32 v91, v66, v67
	v_cvt_pk_bf16_f32 v92, v68, v69
	v_cvt_pk_bf16_f32 v93, v70, v71
	v_cvt_pk_bf16_f32 v94, v72, v73
	v_cvt_pk_bf16_f32 v95, v74, v75
	v_cvt_pk_bf16_f32 v96, v76, v77
	v_cvt_pk_bf16_f32 v97, v78, v79
	v_cvt_pk_bf16_f32 v98, v80, v81
	v_cvt_pk_bf16_f32 v99, v82, v83
	global_store_dwordx4 v16, v[84:87], s[98:99]
	global_store_dwordx4 v17, v[88:91], s[98:99]
	global_store_dwordx4 v18, v[92:95], s[98:99]
	global_store_dwordx4 v19, v[96:99], s[98:99]
	s_waitcnt vmcnt(23)
	ds_write_b32 v14, v20 offset:0
	ds_write_b32 v14, v21 offset:4
	ds_write_b32 v14, v22 offset:8
	ds_write_b32 v14, v23 offset:12
	s_waitcnt vmcnt(22)
	ds_write_b32 v14, v24 offset:1056
	ds_write_b32 v14, v25 offset:1060
	ds_write_b32 v14, v26 offset:1064
	ds_write_b32 v14, v27 offset:1068
	s_waitcnt vmcnt(21)
	ds_write_b32 v14, v28 offset:2112
	ds_write_b32 v14, v29 offset:2116
	ds_write_b32 v14, v30 offset:2120
	ds_write_b32 v14, v31 offset:2124
	s_waitcnt vmcnt(20)
	ds_write_b32 v14, v32 offset:3168
	ds_write_b32 v14, v33 offset:3172
	ds_write_b32 v14, v34 offset:3176
	ds_write_b32 v14, v35 offset:3180
	s_waitcnt vmcnt(19)
	ds_write_b32 v14, v36 offset:4224
	ds_write_b32 v14, v37 offset:4228
	ds_write_b32 v14, v38 offset:4232
	ds_write_b32 v14, v39 offset:4236
	s_waitcnt vmcnt(18)
	ds_write_b32 v14, v40 offset:5280
	ds_write_b32 v14, v41 offset:5284
	ds_write_b32 v14, v42 offset:5288
	ds_write_b32 v14, v43 offset:5292
	s_waitcnt vmcnt(17)
	ds_write_b32 v14, v44 offset:6336
	ds_write_b32 v14, v45 offset:6340
	ds_write_b32 v14, v46 offset:6344
	ds_write_b32 v14, v47 offset:6348
	s_waitcnt vmcnt(16)
	ds_write_b32 v14, v48 offset:7392
	ds_write_b32 v14, v49 offset:7396
	ds_write_b32 v14, v50 offset:7400
	ds_write_b32 v14, v51 offset:7404
	s_add_u32 s95, s94, 0x2800
	s_lshr_b32 vcc_lo, s95, 7
	s_and_b32 vcc_hi, s95, 0x7f
	s_lshl_b32 vcc_lo, vcc_lo, 20
	s_lshl_b32 vcc_hi, vcc_hi, 7
	s_add_u32 s96, s100, vcc_lo
	s_addc_u32 s97, s101, 0
	s_add_u32 s96, s96, vcc_hi
	s_addc_u32 s97, s97, 0
	global_load_dwordx4 v[20:23], v6, s[96:97]
	global_load_dwordx4 v[24:27], v7, s[96:97]
	global_load_dwordx4 v[28:31], v8, s[96:97]
	global_load_dwordx4 v[32:35], v9, s[96:97]
	global_load_dwordx4 v[36:39], v10, s[96:97]
	global_load_dwordx4 v[40:43], v11, s[96:97]
	global_load_dwordx4 v[44:47], v12, s[96:97]
	global_load_dwordx4 v[48:51], v13, s[96:97]
	ds_read2_b32 v[52:53], v15 offset0:0 offset1:33
	ds_read2_b32 v[54:55], v15 offset0:66 offset1:99
	ds_read2_b32 v[56:57], v15 offset0:132 offset1:165
	ds_read2_b32 v[58:59], v15 offset0:198 offset1:231
	ds_read2_b32 v[60:61], v15 offset0:8 offset1:41
	ds_read2_b32 v[62:63], v15 offset0:74 offset1:107
	ds_read2_b32 v[64:65], v15 offset0:140 offset1:173
	ds_read2_b32 v[66:67], v15 offset0:206 offset1:239
	ds_read2_b32 v[68:69], v15 offset0:16 offset1:49
	ds_read2_b32 v[70:71], v15 offset0:82 offset1:115
	ds_read2_b32 v[72:73], v15 offset0:148 offset1:181
	ds_read2_b32 v[74:75], v15 offset0:214 offset1:247
	ds_read2_b32 v[76:77], v15 offset0:24 offset1:57
	ds_read2_b32 v[78:79], v15 offset0:90 offset1:123
	ds_read2_b32 v[80:81], v15 offset0:156 offset1:189
	ds_read2_b32 v[82:83], v15 offset0:222 offset1:255
	s_add_u32 s95, s94, 0x2000
	s_lshr_b32 vcc_lo, s95, 7
	s_and_b32 vcc_hi, s95, 0x7f
	s_mul_i32 vcc_hi, vcc_hi, 0xac000
	s_lshl_b32 vcc_lo, vcc_lo, 7
	s_add_u32 s98, s66, 0x12d00000
	s_addc_u32 s99, s67, 0
	s_add_u32 s98, s98, vcc_hi
	s_addc_u32 s99, s99, 0
	s_add_u32 s98, s98, vcc_lo
	s_addc_u32 s99, s99, 0
	s_waitcnt lgkmcnt(0)
	v_cvt_pk_bf16_f32 v84, v52, v53
	v_cvt_pk_bf16_f32 v85, v54, v55
	v_cvt_pk_bf16_f32 v86, v56, v57
	v_cvt_pk_bf16_f32 v87, v58, v59
	v_cvt_pk_bf16_f32 v88, v60, v61
	v_cvt_pk_bf16_f32 v89, v62, v63
	v_cvt_pk_bf16_f32 v90, v64, v65
	v_cvt_pk_bf16_f32 v91, v66, v67
	v_cvt_pk_bf16_f32 v92, v68, v69
	v_cvt_pk_bf16_f32 v93, v70, v71
	v_cvt_pk_bf16_f32 v94, v72, v73
	v_cvt_pk_bf16_f32 v95, v74, v75
	v_cvt_pk_bf16_f32 v96, v76, v77
	v_cvt_pk_bf16_f32 v97, v78, v79
	v_cvt_pk_bf16_f32 v98, v80, v81
	v_cvt_pk_bf16_f32 v99, v82, v83
	global_store_dwordx4 v16, v[84:87], s[98:99]
	global_store_dwordx4 v17, v[88:91], s[98:99]
	global_store_dwordx4 v18, v[92:95], s[98:99]
	global_store_dwordx4 v19, v[96:99], s[98:99]
	s_waitcnt vmcnt(23)
	ds_write_b32 v14, v100 offset:0
	ds_write_b32 v14, v101 offset:4
	ds_write_b32 v14, v102 offset:8
	ds_write_b32 v14, v103 offset:12
	s_waitcnt vmcnt(22)
	ds_write_b32 v14, v104 offset:1056
	ds_write_b32 v14, v105 offset:1060
	ds_write_b32 v14, v106 offset:1064
	ds_write_b32 v14, v107 offset:1068
	s_waitcnt vmcnt(21)
	ds_write_b32 v14, v108 offset:2112
	ds_write_b32 v14, v109 offset:2116
	ds_write_b32 v14, v110 offset:2120
	ds_write_b32 v14, v111 offset:2124
	s_waitcnt vmcnt(20)
	ds_write_b32 v14, v112 offset:3168
	ds_write_b32 v14, v113 offset:3172
	ds_write_b32 v14, v114 offset:3176
	ds_write_b32 v14, v115 offset:3180
	s_waitcnt vmcnt(19)
	ds_write_b32 v14, v116 offset:4224
	ds_write_b32 v14, v117 offset:4228
	ds_write_b32 v14, v118 offset:4232
	ds_write_b32 v14, v119 offset:4236
	s_waitcnt vmcnt(18)
	ds_write_b32 v14, v120 offset:5280
	ds_write_b32 v14, v121 offset:5284
	ds_write_b32 v14, v122 offset:5288
	ds_write_b32 v14, v123 offset:5292
	s_waitcnt vmcnt(17)
	ds_write_b32 v14, v124 offset:6336
	ds_write_b32 v14, v125 offset:6340
	ds_write_b32 v14, v126 offset:6344
	ds_write_b32 v14, v127 offset:6348
	s_waitcnt vmcnt(16)
	ds_write_b32 v14, v128 offset:7392
	ds_write_b32 v14, v129 offset:7396
	ds_write_b32 v14, v130 offset:7400
	ds_write_b32 v14, v131 offset:7404
	s_add_u32 s95, s94, 0x2c00
	s_lshr_b32 vcc_lo, s95, 7
	s_and_b32 vcc_hi, s95, 0x7f
	s_lshl_b32 vcc_lo, vcc_lo, 20
	s_lshl_b32 vcc_hi, vcc_hi, 7
	s_add_u32 s96, s100, vcc_lo
	s_addc_u32 s97, s101, 0
	s_add_u32 s96, s96, vcc_hi
	s_addc_u32 s97, s97, 0
	global_load_dwordx4 v[100:103], v6, s[96:97]
	global_load_dwordx4 v[104:107], v7, s[96:97]
	global_load_dwordx4 v[108:111], v8, s[96:97]
	global_load_dwordx4 v[112:115], v9, s[96:97]
	global_load_dwordx4 v[116:119], v10, s[96:97]
	global_load_dwordx4 v[120:123], v11, s[96:97]
	global_load_dwordx4 v[124:127], v12, s[96:97]
	global_load_dwordx4 v[128:131], v13, s[96:97]
	ds_read2_b32 v[52:53], v15 offset0:0 offset1:33
	ds_read2_b32 v[54:55], v15 offset0:66 offset1:99
	ds_read2_b32 v[56:57], v15 offset0:132 offset1:165
	ds_read2_b32 v[58:59], v15 offset0:198 offset1:231
	ds_read2_b32 v[60:61], v15 offset0:8 offset1:41
	ds_read2_b32 v[62:63], v15 offset0:74 offset1:107
	ds_read2_b32 v[64:65], v15 offset0:140 offset1:173
	ds_read2_b32 v[66:67], v15 offset0:206 offset1:239
	ds_read2_b32 v[68:69], v15 offset0:16 offset1:49
	ds_read2_b32 v[70:71], v15 offset0:82 offset1:115
	ds_read2_b32 v[72:73], v15 offset0:148 offset1:181
	ds_read2_b32 v[74:75], v15 offset0:214 offset1:247
	ds_read2_b32 v[76:77], v15 offset0:24 offset1:57
	ds_read2_b32 v[78:79], v15 offset0:90 offset1:123
	ds_read2_b32 v[80:81], v15 offset0:156 offset1:189
	ds_read2_b32 v[82:83], v15 offset0:222 offset1:255
	s_add_u32 s95, s94, 0x2400
	s_lshr_b32 vcc_lo, s95, 7
	s_and_b32 vcc_hi, s95, 0x7f
	s_mul_i32 vcc_hi, vcc_hi, 0xac000
	s_lshl_b32 vcc_lo, vcc_lo, 7
	s_add_u32 s98, s66, 0x12d00000
	s_addc_u32 s99, s67, 0
	s_add_u32 s98, s98, vcc_hi
	s_addc_u32 s99, s99, 0
	s_add_u32 s98, s98, vcc_lo
	s_addc_u32 s99, s99, 0
	s_waitcnt lgkmcnt(0)
	v_cvt_pk_bf16_f32 v84, v52, v53
	v_cvt_pk_bf16_f32 v85, v54, v55
	v_cvt_pk_bf16_f32 v86, v56, v57
	v_cvt_pk_bf16_f32 v87, v58, v59
	v_cvt_pk_bf16_f32 v88, v60, v61
	v_cvt_pk_bf16_f32 v89, v62, v63
	v_cvt_pk_bf16_f32 v90, v64, v65
	v_cvt_pk_bf16_f32 v91, v66, v67
	v_cvt_pk_bf16_f32 v92, v68, v69
	v_cvt_pk_bf16_f32 v93, v70, v71
	v_cvt_pk_bf16_f32 v94, v72, v73
	v_cvt_pk_bf16_f32 v95, v74, v75
	v_cvt_pk_bf16_f32 v96, v76, v77
	v_cvt_pk_bf16_f32 v97, v78, v79
	v_cvt_pk_bf16_f32 v98, v80, v81
	v_cvt_pk_bf16_f32 v99, v82, v83
	global_store_dwordx4 v16, v[84:87], s[98:99]
	global_store_dwordx4 v17, v[88:91], s[98:99]
	global_store_dwordx4 v18, v[92:95], s[98:99]
	global_store_dwordx4 v19, v[96:99], s[98:99]
	s_waitcnt vmcnt(23)
	ds_write_b32 v14, v20 offset:0
	ds_write_b32 v14, v21 offset:4
	ds_write_b32 v14, v22 offset:8
	ds_write_b32 v14, v23 offset:12
	s_waitcnt vmcnt(22)
	ds_write_b32 v14, v24 offset:1056
	ds_write_b32 v14, v25 offset:1060
	ds_write_b32 v14, v26 offset:1064
	ds_write_b32 v14, v27 offset:1068
	s_waitcnt vmcnt(21)
	ds_write_b32 v14, v28 offset:2112
	ds_write_b32 v14, v29 offset:2116
	ds_write_b32 v14, v30 offset:2120
	ds_write_b32 v14, v31 offset:2124
	s_waitcnt vmcnt(20)
	ds_write_b32 v14, v32 offset:3168
	ds_write_b32 v14, v33 offset:3172
	ds_write_b32 v14, v34 offset:3176
	ds_write_b32 v14, v35 offset:3180
	s_waitcnt vmcnt(19)
	ds_write_b32 v14, v36 offset:4224
	ds_write_b32 v14, v37 offset:4228
	ds_write_b32 v14, v38 offset:4232
	ds_write_b32 v14, v39 offset:4236
	s_waitcnt vmcnt(18)
	ds_write_b32 v14, v40 offset:5280
	ds_write_b32 v14, v41 offset:5284
	ds_write_b32 v14, v42 offset:5288
	ds_write_b32 v14, v43 offset:5292
	s_waitcnt vmcnt(17)
	ds_write_b32 v14, v44 offset:6336
	ds_write_b32 v14, v45 offset:6340
	ds_write_b32 v14, v46 offset:6344
	ds_write_b32 v14, v47 offset:6348
	s_waitcnt vmcnt(16)
	ds_write_b32 v14, v48 offset:7392
	ds_write_b32 v14, v49 offset:7396
	ds_write_b32 v14, v50 offset:7400
	ds_write_b32 v14, v51 offset:7404
	s_add_u32 s95, s94, 0x3000
	s_lshr_b32 vcc_lo, s95, 7
	s_and_b32 vcc_hi, s95, 0x7f
	s_lshl_b32 vcc_lo, vcc_lo, 20
	s_lshl_b32 vcc_hi, vcc_hi, 7
	s_add_u32 s96, s100, vcc_lo
	s_addc_u32 s97, s101, 0
	s_add_u32 s96, s96, vcc_hi
	s_addc_u32 s97, s97, 0
	global_load_dwordx4 v[20:23], v6, s[96:97]
	global_load_dwordx4 v[24:27], v7, s[96:97]
	global_load_dwordx4 v[28:31], v8, s[96:97]
	global_load_dwordx4 v[32:35], v9, s[96:97]
	global_load_dwordx4 v[36:39], v10, s[96:97]
	global_load_dwordx4 v[40:43], v11, s[96:97]
	global_load_dwordx4 v[44:47], v12, s[96:97]
	global_load_dwordx4 v[48:51], v13, s[96:97]
	ds_read2_b32 v[52:53], v15 offset0:0 offset1:33
	ds_read2_b32 v[54:55], v15 offset0:66 offset1:99
	ds_read2_b32 v[56:57], v15 offset0:132 offset1:165
	ds_read2_b32 v[58:59], v15 offset0:198 offset1:231
	ds_read2_b32 v[60:61], v15 offset0:8 offset1:41
	ds_read2_b32 v[62:63], v15 offset0:74 offset1:107
	ds_read2_b32 v[64:65], v15 offset0:140 offset1:173
	ds_read2_b32 v[66:67], v15 offset0:206 offset1:239
	ds_read2_b32 v[68:69], v15 offset0:16 offset1:49
	ds_read2_b32 v[70:71], v15 offset0:82 offset1:115
	ds_read2_b32 v[72:73], v15 offset0:148 offset1:181
	ds_read2_b32 v[74:75], v15 offset0:214 offset1:247
	ds_read2_b32 v[76:77], v15 offset0:24 offset1:57
	ds_read2_b32 v[78:79], v15 offset0:90 offset1:123
	ds_read2_b32 v[80:81], v15 offset0:156 offset1:189
	ds_read2_b32 v[82:83], v15 offset0:222 offset1:255
	s_add_u32 s95, s94, 0x2800
	s_lshr_b32 vcc_lo, s95, 7
	s_and_b32 vcc_hi, s95, 0x7f
	s_mul_i32 vcc_hi, vcc_hi, 0xac000
	s_lshl_b32 vcc_lo, vcc_lo, 7
	s_add_u32 s98, s66, 0x12d00000
	s_addc_u32 s99, s67, 0
	s_add_u32 s98, s98, vcc_hi
	s_addc_u32 s99, s99, 0
	s_add_u32 s98, s98, vcc_lo
	s_addc_u32 s99, s99, 0
	s_waitcnt lgkmcnt(0)
	v_cvt_pk_bf16_f32 v84, v52, v53
	v_cvt_pk_bf16_f32 v85, v54, v55
	v_cvt_pk_bf16_f32 v86, v56, v57
	v_cvt_pk_bf16_f32 v87, v58, v59
	v_cvt_pk_bf16_f32 v88, v60, v61
	v_cvt_pk_bf16_f32 v89, v62, v63
	v_cvt_pk_bf16_f32 v90, v64, v65
	v_cvt_pk_bf16_f32 v91, v66, v67
	v_cvt_pk_bf16_f32 v92, v68, v69
	v_cvt_pk_bf16_f32 v93, v70, v71
	v_cvt_pk_bf16_f32 v94, v72, v73
	v_cvt_pk_bf16_f32 v95, v74, v75
	v_cvt_pk_bf16_f32 v96, v76, v77
	v_cvt_pk_bf16_f32 v97, v78, v79
	v_cvt_pk_bf16_f32 v98, v80, v81
	v_cvt_pk_bf16_f32 v99, v82, v83
	global_store_dwordx4 v16, v[84:87], s[98:99]
	global_store_dwordx4 v17, v[88:91], s[98:99]
	global_store_dwordx4 v18, v[92:95], s[98:99]
	global_store_dwordx4 v19, v[96:99], s[98:99]
	s_waitcnt vmcnt(23)
	ds_write_b32 v14, v100 offset:0
	ds_write_b32 v14, v101 offset:4
	ds_write_b32 v14, v102 offset:8
	ds_write_b32 v14, v103 offset:12
	s_waitcnt vmcnt(22)
	ds_write_b32 v14, v104 offset:1056
	ds_write_b32 v14, v105 offset:1060
	ds_write_b32 v14, v106 offset:1064
	ds_write_b32 v14, v107 offset:1068
	s_waitcnt vmcnt(21)
	ds_write_b32 v14, v108 offset:2112
	ds_write_b32 v14, v109 offset:2116
	ds_write_b32 v14, v110 offset:2120
	ds_write_b32 v14, v111 offset:2124
	s_waitcnt vmcnt(20)
	ds_write_b32 v14, v112 offset:3168
	ds_write_b32 v14, v113 offset:3172
	ds_write_b32 v14, v114 offset:3176
	ds_write_b32 v14, v115 offset:3180
	s_waitcnt vmcnt(19)
	ds_write_b32 v14, v116 offset:4224
	ds_write_b32 v14, v117 offset:4228
	ds_write_b32 v14, v118 offset:4232
	ds_write_b32 v14, v119 offset:4236
	s_waitcnt vmcnt(18)
	ds_write_b32 v14, v120 offset:5280
	ds_write_b32 v14, v121 offset:5284
	ds_write_b32 v14, v122 offset:5288
	ds_write_b32 v14, v123 offset:5292
	s_waitcnt vmcnt(17)
	ds_write_b32 v14, v124 offset:6336
	ds_write_b32 v14, v125 offset:6340
	ds_write_b32 v14, v126 offset:6344
	ds_write_b32 v14, v127 offset:6348
	s_waitcnt vmcnt(16)
	ds_write_b32 v14, v128 offset:7392
	ds_write_b32 v14, v129 offset:7396
	ds_write_b32 v14, v130 offset:7400
	ds_write_b32 v14, v131 offset:7404
	s_add_u32 s95, s94, 0x3400
	s_lshr_b32 vcc_lo, s95, 7
	s_and_b32 vcc_hi, s95, 0x7f
	s_lshl_b32 vcc_lo, vcc_lo, 20
	s_lshl_b32 vcc_hi, vcc_hi, 7
	s_add_u32 s96, s100, vcc_lo
	s_addc_u32 s97, s101, 0
	s_add_u32 s96, s96, vcc_hi
	s_addc_u32 s97, s97, 0
	global_load_dwordx4 v[100:103], v6, s[96:97]
	global_load_dwordx4 v[104:107], v7, s[96:97]
	global_load_dwordx4 v[108:111], v8, s[96:97]
	global_load_dwordx4 v[112:115], v9, s[96:97]
	global_load_dwordx4 v[116:119], v10, s[96:97]
	global_load_dwordx4 v[120:123], v11, s[96:97]
	global_load_dwordx4 v[124:127], v12, s[96:97]
	global_load_dwordx4 v[128:131], v13, s[96:97]
	ds_read2_b32 v[52:53], v15 offset0:0 offset1:33
	ds_read2_b32 v[54:55], v15 offset0:66 offset1:99
	ds_read2_b32 v[56:57], v15 offset0:132 offset1:165
	ds_read2_b32 v[58:59], v15 offset0:198 offset1:231
	ds_read2_b32 v[60:61], v15 offset0:8 offset1:41
	ds_read2_b32 v[62:63], v15 offset0:74 offset1:107
	ds_read2_b32 v[64:65], v15 offset0:140 offset1:173
	ds_read2_b32 v[66:67], v15 offset0:206 offset1:239
	ds_read2_b32 v[68:69], v15 offset0:16 offset1:49
	ds_read2_b32 v[70:71], v15 offset0:82 offset1:115
	ds_read2_b32 v[72:73], v15 offset0:148 offset1:181
	ds_read2_b32 v[74:75], v15 offset0:214 offset1:247
	ds_read2_b32 v[76:77], v15 offset0:24 offset1:57
	ds_read2_b32 v[78:79], v15 offset0:90 offset1:123
	ds_read2_b32 v[80:81], v15 offset0:156 offset1:189
	ds_read2_b32 v[82:83], v15 offset0:222 offset1:255
	s_add_u32 s95, s94, 0x2c00
	s_lshr_b32 vcc_lo, s95, 7
	s_and_b32 vcc_hi, s95, 0x7f
	s_mul_i32 vcc_hi, vcc_hi, 0xac000
	s_lshl_b32 vcc_lo, vcc_lo, 7
	s_add_u32 s98, s66, 0x12d00000
	s_addc_u32 s99, s67, 0
	s_add_u32 s98, s98, vcc_hi
	s_addc_u32 s99, s99, 0
	s_add_u32 s98, s98, vcc_lo
	s_addc_u32 s99, s99, 0
	s_waitcnt lgkmcnt(0)
	v_cvt_pk_bf16_f32 v84, v52, v53
	v_cvt_pk_bf16_f32 v85, v54, v55
	v_cvt_pk_bf16_f32 v86, v56, v57
	v_cvt_pk_bf16_f32 v87, v58, v59
	v_cvt_pk_bf16_f32 v88, v60, v61
	v_cvt_pk_bf16_f32 v89, v62, v63
	v_cvt_pk_bf16_f32 v90, v64, v65
	v_cvt_pk_bf16_f32 v91, v66, v67
	v_cvt_pk_bf16_f32 v92, v68, v69
	v_cvt_pk_bf16_f32 v93, v70, v71
	v_cvt_pk_bf16_f32 v94, v72, v73
	v_cvt_pk_bf16_f32 v95, v74, v75
	v_cvt_pk_bf16_f32 v96, v76, v77
	v_cvt_pk_bf16_f32 v97, v78, v79
	v_cvt_pk_bf16_f32 v98, v80, v81
	v_cvt_pk_bf16_f32 v99, v82, v83
	global_store_dwordx4 v16, v[84:87], s[98:99]
	global_store_dwordx4 v17, v[88:91], s[98:99]
	global_store_dwordx4 v18, v[92:95], s[98:99]
	global_store_dwordx4 v19, v[96:99], s[98:99]
	s_waitcnt vmcnt(23)
	ds_write_b32 v14, v20 offset:0
	ds_write_b32 v14, v21 offset:4
	ds_write_b32 v14, v22 offset:8
	ds_write_b32 v14, v23 offset:12
	s_waitcnt vmcnt(22)
	ds_write_b32 v14, v24 offset:1056
	ds_write_b32 v14, v25 offset:1060
	ds_write_b32 v14, v26 offset:1064
	ds_write_b32 v14, v27 offset:1068
	s_waitcnt vmcnt(21)
	ds_write_b32 v14, v28 offset:2112
	ds_write_b32 v14, v29 offset:2116
	ds_write_b32 v14, v30 offset:2120
	ds_write_b32 v14, v31 offset:2124
	s_waitcnt vmcnt(20)
	ds_write_b32 v14, v32 offset:3168
	ds_write_b32 v14, v33 offset:3172
	ds_write_b32 v14, v34 offset:3176
	ds_write_b32 v14, v35 offset:3180
	s_waitcnt vmcnt(19)
	ds_write_b32 v14, v36 offset:4224
	ds_write_b32 v14, v37 offset:4228
	ds_write_b32 v14, v38 offset:4232
	ds_write_b32 v14, v39 offset:4236
	s_waitcnt vmcnt(18)
	ds_write_b32 v14, v40 offset:5280
	ds_write_b32 v14, v41 offset:5284
	ds_write_b32 v14, v42 offset:5288
	ds_write_b32 v14, v43 offset:5292
	s_waitcnt vmcnt(17)
	ds_write_b32 v14, v44 offset:6336
	ds_write_b32 v14, v45 offset:6340
	ds_write_b32 v14, v46 offset:6344
	ds_write_b32 v14, v47 offset:6348
	s_waitcnt vmcnt(16)
	ds_write_b32 v14, v48 offset:7392
	ds_write_b32 v14, v49 offset:7396
	ds_write_b32 v14, v50 offset:7400
	ds_write_b32 v14, v51 offset:7404
	s_add_u32 s95, s94, 0x3800
	s_lshr_b32 vcc_lo, s95, 7
	s_and_b32 vcc_hi, s95, 0x7f
	s_lshl_b32 vcc_lo, vcc_lo, 20
	s_lshl_b32 vcc_hi, vcc_hi, 7
	s_add_u32 s96, s100, vcc_lo
	s_addc_u32 s97, s101, 0
	s_add_u32 s96, s96, vcc_hi
	s_addc_u32 s97, s97, 0
	global_load_dwordx4 v[20:23], v6, s[96:97]
	global_load_dwordx4 v[24:27], v7, s[96:97]
	global_load_dwordx4 v[28:31], v8, s[96:97]
	global_load_dwordx4 v[32:35], v9, s[96:97]
	global_load_dwordx4 v[36:39], v10, s[96:97]
	global_load_dwordx4 v[40:43], v11, s[96:97]
	global_load_dwordx4 v[44:47], v12, s[96:97]
	global_load_dwordx4 v[48:51], v13, s[96:97]
	ds_read2_b32 v[52:53], v15 offset0:0 offset1:33
	ds_read2_b32 v[54:55], v15 offset0:66 offset1:99
	ds_read2_b32 v[56:57], v15 offset0:132 offset1:165
	ds_read2_b32 v[58:59], v15 offset0:198 offset1:231
	ds_read2_b32 v[60:61], v15 offset0:8 offset1:41
	ds_read2_b32 v[62:63], v15 offset0:74 offset1:107
	ds_read2_b32 v[64:65], v15 offset0:140 offset1:173
	ds_read2_b32 v[66:67], v15 offset0:206 offset1:239
	ds_read2_b32 v[68:69], v15 offset0:16 offset1:49
	ds_read2_b32 v[70:71], v15 offset0:82 offset1:115
	ds_read2_b32 v[72:73], v15 offset0:148 offset1:181
	ds_read2_b32 v[74:75], v15 offset0:214 offset1:247
	ds_read2_b32 v[76:77], v15 offset0:24 offset1:57
	ds_read2_b32 v[78:79], v15 offset0:90 offset1:123
	ds_read2_b32 v[80:81], v15 offset0:156 offset1:189
	ds_read2_b32 v[82:83], v15 offset0:222 offset1:255
	s_add_u32 s95, s94, 0x3000
	s_lshr_b32 vcc_lo, s95, 7
	s_and_b32 vcc_hi, s95, 0x7f
	s_mul_i32 vcc_hi, vcc_hi, 0xac000
	s_lshl_b32 vcc_lo, vcc_lo, 7
	s_add_u32 s98, s66, 0x12d00000
	s_addc_u32 s99, s67, 0
	s_add_u32 s98, s98, vcc_hi
	s_addc_u32 s99, s99, 0
	s_add_u32 s98, s98, vcc_lo
	s_addc_u32 s99, s99, 0
	s_waitcnt lgkmcnt(0)
	v_cvt_pk_bf16_f32 v84, v52, v53
	v_cvt_pk_bf16_f32 v85, v54, v55
	v_cvt_pk_bf16_f32 v86, v56, v57
	v_cvt_pk_bf16_f32 v87, v58, v59
	v_cvt_pk_bf16_f32 v88, v60, v61
	v_cvt_pk_bf16_f32 v89, v62, v63
	v_cvt_pk_bf16_f32 v90, v64, v65
	v_cvt_pk_bf16_f32 v91, v66, v67
	v_cvt_pk_bf16_f32 v92, v68, v69
	v_cvt_pk_bf16_f32 v93, v70, v71
	v_cvt_pk_bf16_f32 v94, v72, v73
	v_cvt_pk_bf16_f32 v95, v74, v75
	v_cvt_pk_bf16_f32 v96, v76, v77
	v_cvt_pk_bf16_f32 v97, v78, v79
	v_cvt_pk_bf16_f32 v98, v80, v81
	v_cvt_pk_bf16_f32 v99, v82, v83
	global_store_dwordx4 v16, v[84:87], s[98:99]
	global_store_dwordx4 v17, v[88:91], s[98:99]
	global_store_dwordx4 v18, v[92:95], s[98:99]
	global_store_dwordx4 v19, v[96:99], s[98:99]
	s_waitcnt vmcnt(23)
	ds_write_b32 v14, v100 offset:0
	ds_write_b32 v14, v101 offset:4
	ds_write_b32 v14, v102 offset:8
	ds_write_b32 v14, v103 offset:12
	s_waitcnt vmcnt(22)
	ds_write_b32 v14, v104 offset:1056
	ds_write_b32 v14, v105 offset:1060
	ds_write_b32 v14, v106 offset:1064
	ds_write_b32 v14, v107 offset:1068
	s_waitcnt vmcnt(21)
	ds_write_b32 v14, v108 offset:2112
	ds_write_b32 v14, v109 offset:2116
	ds_write_b32 v14, v110 offset:2120
	ds_write_b32 v14, v111 offset:2124
	s_waitcnt vmcnt(20)
	ds_write_b32 v14, v112 offset:3168
	ds_write_b32 v14, v113 offset:3172
	ds_write_b32 v14, v114 offset:3176
	ds_write_b32 v14, v115 offset:3180
	s_waitcnt vmcnt(19)
	ds_write_b32 v14, v116 offset:4224
	ds_write_b32 v14, v117 offset:4228
	ds_write_b32 v14, v118 offset:4232
	ds_write_b32 v14, v119 offset:4236
	s_waitcnt vmcnt(18)
	ds_write_b32 v14, v120 offset:5280
	ds_write_b32 v14, v121 offset:5284
	ds_write_b32 v14, v122 offset:5288
	ds_write_b32 v14, v123 offset:5292
	s_waitcnt vmcnt(17)
	ds_write_b32 v14, v124 offset:6336
	ds_write_b32 v14, v125 offset:6340
	ds_write_b32 v14, v126 offset:6344
	ds_write_b32 v14, v127 offset:6348
	s_waitcnt vmcnt(16)
	ds_write_b32 v14, v128 offset:7392
	ds_write_b32 v14, v129 offset:7396
	ds_write_b32 v14, v130 offset:7400
	ds_write_b32 v14, v131 offset:7404
	s_add_u32 s95, s94, 0x3c00
	s_lshr_b32 vcc_lo, s95, 7
	s_and_b32 vcc_hi, s95, 0x7f
	s_lshl_b32 vcc_lo, vcc_lo, 20
	s_lshl_b32 vcc_hi, vcc_hi, 7
	s_add_u32 s96, s100, vcc_lo
	s_addc_u32 s97, s101, 0
	s_add_u32 s96, s96, vcc_hi
	s_addc_u32 s97, s97, 0
	global_load_dwordx4 v[100:103], v6, s[96:97]
	global_load_dwordx4 v[104:107], v7, s[96:97]
	global_load_dwordx4 v[108:111], v8, s[96:97]
	global_load_dwordx4 v[112:115], v9, s[96:97]
	global_load_dwordx4 v[116:119], v10, s[96:97]
	global_load_dwordx4 v[120:123], v11, s[96:97]
	global_load_dwordx4 v[124:127], v12, s[96:97]
	global_load_dwordx4 v[128:131], v13, s[96:97]
	ds_read2_b32 v[52:53], v15 offset0:0 offset1:33
	ds_read2_b32 v[54:55], v15 offset0:66 offset1:99
	ds_read2_b32 v[56:57], v15 offset0:132 offset1:165
	ds_read2_b32 v[58:59], v15 offset0:198 offset1:231
	ds_read2_b32 v[60:61], v15 offset0:8 offset1:41
	ds_read2_b32 v[62:63], v15 offset0:74 offset1:107
	ds_read2_b32 v[64:65], v15 offset0:140 offset1:173
	ds_read2_b32 v[66:67], v15 offset0:206 offset1:239
	ds_read2_b32 v[68:69], v15 offset0:16 offset1:49
	ds_read2_b32 v[70:71], v15 offset0:82 offset1:115
	ds_read2_b32 v[72:73], v15 offset0:148 offset1:181
	ds_read2_b32 v[74:75], v15 offset0:214 offset1:247
	ds_read2_b32 v[76:77], v15 offset0:24 offset1:57
	ds_read2_b32 v[78:79], v15 offset0:90 offset1:123
	ds_read2_b32 v[80:81], v15 offset0:156 offset1:189
	ds_read2_b32 v[82:83], v15 offset0:222 offset1:255
	s_add_u32 s95, s94, 0x3400
	s_lshr_b32 vcc_lo, s95, 7
	s_and_b32 vcc_hi, s95, 0x7f
	s_mul_i32 vcc_hi, vcc_hi, 0xac000
	s_lshl_b32 vcc_lo, vcc_lo, 7
	s_add_u32 s98, s66, 0x12d00000
	s_addc_u32 s99, s67, 0
	s_add_u32 s98, s98, vcc_hi
	s_addc_u32 s99, s99, 0
	s_add_u32 s98, s98, vcc_lo
	s_addc_u32 s99, s99, 0
	s_waitcnt lgkmcnt(0)
	v_cvt_pk_bf16_f32 v84, v52, v53
	v_cvt_pk_bf16_f32 v85, v54, v55
	v_cvt_pk_bf16_f32 v86, v56, v57
	v_cvt_pk_bf16_f32 v87, v58, v59
	v_cvt_pk_bf16_f32 v88, v60, v61
	v_cvt_pk_bf16_f32 v89, v62, v63
	v_cvt_pk_bf16_f32 v90, v64, v65
	v_cvt_pk_bf16_f32 v91, v66, v67
	v_cvt_pk_bf16_f32 v92, v68, v69
	v_cvt_pk_bf16_f32 v93, v70, v71
	v_cvt_pk_bf16_f32 v94, v72, v73
	v_cvt_pk_bf16_f32 v95, v74, v75
	v_cvt_pk_bf16_f32 v96, v76, v77
	v_cvt_pk_bf16_f32 v97, v78, v79
	v_cvt_pk_bf16_f32 v98, v80, v81
	v_cvt_pk_bf16_f32 v99, v82, v83
	global_store_dwordx4 v16, v[84:87], s[98:99]
	global_store_dwordx4 v17, v[88:91], s[98:99]
	global_store_dwordx4 v18, v[92:95], s[98:99]
	global_store_dwordx4 v19, v[96:99], s[98:99]
	s_waitcnt vmcnt(23)
	ds_write_b32 v14, v20 offset:0
	ds_write_b32 v14, v21 offset:4
	ds_write_b32 v14, v22 offset:8
	ds_write_b32 v14, v23 offset:12
	s_waitcnt vmcnt(22)
	ds_write_b32 v14, v24 offset:1056
	ds_write_b32 v14, v25 offset:1060
	ds_write_b32 v14, v26 offset:1064
	ds_write_b32 v14, v27 offset:1068
	s_waitcnt vmcnt(21)
	ds_write_b32 v14, v28 offset:2112
	ds_write_b32 v14, v29 offset:2116
	ds_write_b32 v14, v30 offset:2120
	ds_write_b32 v14, v31 offset:2124
	s_waitcnt vmcnt(20)
	ds_write_b32 v14, v32 offset:3168
	ds_write_b32 v14, v33 offset:3172
	ds_write_b32 v14, v34 offset:3176
	ds_write_b32 v14, v35 offset:3180
	s_waitcnt vmcnt(19)
	ds_write_b32 v14, v36 offset:4224
	ds_write_b32 v14, v37 offset:4228
	ds_write_b32 v14, v38 offset:4232
	ds_write_b32 v14, v39 offset:4236
	s_waitcnt vmcnt(18)
	ds_write_b32 v14, v40 offset:5280
	ds_write_b32 v14, v41 offset:5284
	ds_write_b32 v14, v42 offset:5288
	ds_write_b32 v14, v43 offset:5292
	s_waitcnt vmcnt(17)
	ds_write_b32 v14, v44 offset:6336
	ds_write_b32 v14, v45 offset:6340
	ds_write_b32 v14, v46 offset:6344
	ds_write_b32 v14, v47 offset:6348
	s_waitcnt vmcnt(16)
	ds_write_b32 v14, v48 offset:7392
	ds_write_b32 v14, v49 offset:7396
	ds_write_b32 v14, v50 offset:7400
	ds_write_b32 v14, v51 offset:7404
	ds_read2_b32 v[52:53], v15 offset0:0 offset1:33
	ds_read2_b32 v[54:55], v15 offset0:66 offset1:99
	ds_read2_b32 v[56:57], v15 offset0:132 offset1:165
	ds_read2_b32 v[58:59], v15 offset0:198 offset1:231
	ds_read2_b32 v[60:61], v15 offset0:8 offset1:41
	ds_read2_b32 v[62:63], v15 offset0:74 offset1:107
	ds_read2_b32 v[64:65], v15 offset0:140 offset1:173
	ds_read2_b32 v[66:67], v15 offset0:206 offset1:239
	ds_read2_b32 v[68:69], v15 offset0:16 offset1:49
	ds_read2_b32 v[70:71], v15 offset0:82 offset1:115
	ds_read2_b32 v[72:73], v15 offset0:148 offset1:181
	ds_read2_b32 v[74:75], v15 offset0:214 offset1:247
	ds_read2_b32 v[76:77], v15 offset0:24 offset1:57
	ds_read2_b32 v[78:79], v15 offset0:90 offset1:123
	ds_read2_b32 v[80:81], v15 offset0:156 offset1:189
	ds_read2_b32 v[82:83], v15 offset0:222 offset1:255
	s_add_u32 s95, s94, 0x3800
	s_lshr_b32 vcc_lo, s95, 7
	s_and_b32 vcc_hi, s95, 0x7f
	s_mul_i32 vcc_hi, vcc_hi, 0xac000
	s_lshl_b32 vcc_lo, vcc_lo, 7
	s_add_u32 s98, s66, 0x12d00000
	s_addc_u32 s99, s67, 0
	s_add_u32 s98, s98, vcc_hi
	s_addc_u32 s99, s99, 0
	s_add_u32 s98, s98, vcc_lo
	s_addc_u32 s99, s99, 0
	s_waitcnt lgkmcnt(0)
	v_cvt_pk_bf16_f32 v84, v52, v53
	v_cvt_pk_bf16_f32 v85, v54, v55
	v_cvt_pk_bf16_f32 v86, v56, v57
	v_cvt_pk_bf16_f32 v87, v58, v59
	v_cvt_pk_bf16_f32 v88, v60, v61
	v_cvt_pk_bf16_f32 v89, v62, v63
	v_cvt_pk_bf16_f32 v90, v64, v65
	v_cvt_pk_bf16_f32 v91, v66, v67
	v_cvt_pk_bf16_f32 v92, v68, v69
	v_cvt_pk_bf16_f32 v93, v70, v71
	v_cvt_pk_bf16_f32 v94, v72, v73
	v_cvt_pk_bf16_f32 v95, v74, v75
	v_cvt_pk_bf16_f32 v96, v76, v77
	v_cvt_pk_bf16_f32 v97, v78, v79
	v_cvt_pk_bf16_f32 v98, v80, v81
	v_cvt_pk_bf16_f32 v99, v82, v83
	global_store_dwordx4 v16, v[84:87], s[98:99]
	global_store_dwordx4 v17, v[88:91], s[98:99]
	global_store_dwordx4 v18, v[92:95], s[98:99]
	global_store_dwordx4 v19, v[96:99], s[98:99]
	s_waitcnt vmcnt(15)
	ds_write_b32 v14, v100 offset:0
	ds_write_b32 v14, v101 offset:4
	ds_write_b32 v14, v102 offset:8
	ds_write_b32 v14, v103 offset:12
	s_waitcnt vmcnt(14)
	ds_write_b32 v14, v104 offset:1056
	ds_write_b32 v14, v105 offset:1060
	ds_write_b32 v14, v106 offset:1064
	ds_write_b32 v14, v107 offset:1068
	s_waitcnt vmcnt(13)
	ds_write_b32 v14, v108 offset:2112
	ds_write_b32 v14, v109 offset:2116
	ds_write_b32 v14, v110 offset:2120
	ds_write_b32 v14, v111 offset:2124
	s_waitcnt vmcnt(12)
	ds_write_b32 v14, v112 offset:3168
	ds_write_b32 v14, v113 offset:3172
	ds_write_b32 v14, v114 offset:3176
	ds_write_b32 v14, v115 offset:3180
	s_waitcnt vmcnt(11)
	ds_write_b32 v14, v116 offset:4224
	ds_write_b32 v14, v117 offset:4228
	ds_write_b32 v14, v118 offset:4232
	ds_write_b32 v14, v119 offset:4236
	s_waitcnt vmcnt(10)
	ds_write_b32 v14, v120 offset:5280
	ds_write_b32 v14, v121 offset:5284
	ds_write_b32 v14, v122 offset:5288
	ds_write_b32 v14, v123 offset:5292
	s_waitcnt vmcnt(9)
	ds_write_b32 v14, v124 offset:6336
	ds_write_b32 v14, v125 offset:6340
	ds_write_b32 v14, v126 offset:6344
	ds_write_b32 v14, v127 offset:6348
	s_waitcnt vmcnt(8)
	ds_write_b32 v14, v128 offset:7392
	ds_write_b32 v14, v129 offset:7396
	ds_write_b32 v14, v130 offset:7400
	ds_write_b32 v14, v131 offset:7404
	ds_read2_b32 v[52:53], v15 offset0:0 offset1:33
	ds_read2_b32 v[54:55], v15 offset0:66 offset1:99
	ds_read2_b32 v[56:57], v15 offset0:132 offset1:165
	ds_read2_b32 v[58:59], v15 offset0:198 offset1:231
	ds_read2_b32 v[60:61], v15 offset0:8 offset1:41
	ds_read2_b32 v[62:63], v15 offset0:74 offset1:107
	ds_read2_b32 v[64:65], v15 offset0:140 offset1:173
	ds_read2_b32 v[66:67], v15 offset0:206 offset1:239
	ds_read2_b32 v[68:69], v15 offset0:16 offset1:49
	ds_read2_b32 v[70:71], v15 offset0:82 offset1:115
	ds_read2_b32 v[72:73], v15 offset0:148 offset1:181
	ds_read2_b32 v[74:75], v15 offset0:214 offset1:247
	ds_read2_b32 v[76:77], v15 offset0:24 offset1:57
	ds_read2_b32 v[78:79], v15 offset0:90 offset1:123
	ds_read2_b32 v[80:81], v15 offset0:156 offset1:189
	ds_read2_b32 v[82:83], v15 offset0:222 offset1:255
	s_add_u32 s95, s94, 0x3c00
	s_lshr_b32 vcc_lo, s95, 7
	s_and_b32 vcc_hi, s95, 0x7f
	s_mul_i32 vcc_hi, vcc_hi, 0xac000
	s_lshl_b32 vcc_lo, vcc_lo, 7
	s_add_u32 s98, s66, 0x12d00000
	s_addc_u32 s99, s67, 0
	s_add_u32 s98, s98, vcc_hi
	s_addc_u32 s99, s99, 0
	s_add_u32 s98, s98, vcc_lo
	s_addc_u32 s99, s99, 0
	s_waitcnt lgkmcnt(0)
	v_cvt_pk_bf16_f32 v84, v52, v53
	v_cvt_pk_bf16_f32 v85, v54, v55
	v_cvt_pk_bf16_f32 v86, v56, v57
	v_cvt_pk_bf16_f32 v87, v58, v59
	v_cvt_pk_bf16_f32 v88, v60, v61
	v_cvt_pk_bf16_f32 v89, v62, v63
	v_cvt_pk_bf16_f32 v90, v64, v65
	v_cvt_pk_bf16_f32 v91, v66, v67
	v_cvt_pk_bf16_f32 v92, v68, v69
	v_cvt_pk_bf16_f32 v93, v70, v71
	v_cvt_pk_bf16_f32 v94, v72, v73
	v_cvt_pk_bf16_f32 v95, v74, v75
	v_cvt_pk_bf16_f32 v96, v76, v77
	v_cvt_pk_bf16_f32 v97, v78, v79
	v_cvt_pk_bf16_f32 v98, v80, v81
	v_cvt_pk_bf16_f32 v99, v82, v83
	global_store_dwordx4 v16, v[84:87], s[98:99]
	global_store_dwordx4 v17, v[88:91], s[98:99]
	global_store_dwordx4 v18, v[92:95], s[98:99]
	global_store_dwordx4 v19, v[96:99], s[98:99]
